# v102 + K-loops: third/fourth LDS-DMA addresses of segment 2 kept in spare v[244:247] so segment 4 uses offset:128 twins (2 fewer 64-bit VALU + 2 SALU per 2 K-tiles)
# speedup vs baseline: 1.0078x; 1.0078x over previous
; #define PG8_STAGE(bufoff, gbase, voff) do { _Pragma("unroll") for (int _i = 0; _i < 2; ++_i) \
;         __builtin_amdgcn_global_load_lds((const unsigned*)((const char*)(gbase) + (voff)[_i]), (PG8_LAS unsigned*)(lds + (bufoff) + ldsw + _i * 8192), 16, 0, 0); } while (0)
; #define PG8_LDA(dst, b, h) do { _Pragma("unroll") for (int m = 0; m < 4; ++m) _Pragma("unroll") for (int k = 0; k < 2; ++k) dst[m][k] = *(const PG8_LAS bf16x8*)(lds + PG8_SA(b, h) + aoff + m * 2048 + k * 1024); } while (0)
; #define PG8_LDB(dst, b, h) do { _Pragma("unroll") for (int n = 0; n < 2; ++n) _Pragma("unroll") for (int k = 0; k < 2; ++k) dst[n][k] = *(const PG8_LAS bf16x8*)(lds + PG8_SB(b, h) + boff + n * 2048 + k * 1024); } while (0)
; #define PG8_WAIT_V(n) asm volatile("s_waitcnt vmcnt(" #n ")" ::: "memory")
; #define PG8_WAIT_L(n) asm volatile("s_waitcnt lgkmcnt(" #n ")" ::: "memory")
; #define PG8_BAR __builtin_amdgcn_s_barrier()
; #define PG8_SCHED __builtin_amdgcn_sched_barrier(0)
; template <class Epi, class Sched, bool ALIGN_EPI = false, bool SP2 = false>
; __device__ __forceinline__ void gemm_phase(PG8_LAS unsigned char* lds, const Gemm g, const Sched& S, const Epi& E) {
;     ...
;         const bool has_next = S.next(ui + 1, nxt);
;         const char* nA = has_next ? (const char*)g.A + (size_t)nxt.pm * tstep : cA; const char* nB = has_next ? (const char*)g.Bt + (size_t)nxt.pn * tstep : cB;
;         for (int t = 0; t < nt; t += 2) {
;             const bool last = (t == nt - 2);
;             const char* a1 = cA + (size_t)(t + 1) * kstep;
;             const char* a2 = last ? nA : cA + (size_t)(t + 2) * kstep; const char* b2 = last ? nB : cB + (size_t)(t + 2) * kstep;
;             const char* a3 = a2 + kstep; const char* b3 = b2 + kstep;
;             if (last && has_next) S.a_ready(nxt);
;             if constexpr (SP2) {
;             PG8_LDB(B0, 0, 0); PG8_LDB(B1, 0, 1); PG8_SCHED; PG8_LDA(At, 0, 0); PG8_STAGE(PG8_SA(1, 1), a1 + hstep, voffA);
;             PG8_WAIT_V(8); PG8_WAIT_L(0); PG8_BAR; PG8_MMA(0, 0, At, B0); PG8_MMA(0, 1, At, B1); PG8_BAR; PG8_SCHED;
;             PG8_LDA(At, 0, 1); PG8_STAGE(PG8_SB(0, 0), b2, voffB); PG8_STAGE(PG8_SB(0, 1), b2 + hstep, voffB); PG8_STAGE(PG8_SA(0, 0), a2, voffA);
;             PG8_WAIT_V(8); PG8_WAIT_L(0); PG8_BAR; PG8_MMA(1, 0, At, B0); PG8_MMA(1, 1, At, B1); PG8_BAR; PG8_SCHED;
.LBB0_99:
	s_ashr_i32 s21, s20, 31
	s_lshl_b64 s[24:25], s[20:21], 19
	s_add_u32 s24, s35, s24
	s_addc_u32 s25, s38, s25
	s_and_b64 s[26:27], s[4:5], exec
	s_cselect_b32 s3, s25, s9
	s_cselect_b32 s7, s24, s8
	s_ashr_i32 s23, s22, 31
	s_lshl_b64 s[26:27], s[22:23], 19
	s_add_u32 s26, s39, s26
	s_addc_u32 s27, s40, s27
	s_and_b64 s[30:31], s[4:5], exec
	s_cselect_b32 s11, s27, s29
	s_cselect_b32 s21, s26, s28
	s_add_u32 s8, s8, 0x40080
	s_addc_u32 s9, s9, 0
	s_add_u32 s23, s28, 0x100
	s_addc_u32 s44, s29, 0
	s_mov_b32 s45, -2
	s_add_u32 s28, s8, 0xfffc0080
	s_addc_u32 s29, s9, -1
	s_cmp_eq_u32 s45, 12
	s_cselect_b32 s31, s3, s29
	s_cselect_b32 s30, s7, s28
	s_cselect_b32 s29, s11, s44
	s_cselect_b32 s28, s21, s23
	ds_read_b128 v[132:135], v204
	ds_read_b128 v[136:139], v204 offset:1024
	ds_read_b128 v[140:143], v204 offset:2048
	ds_read_b128 v[144:147], v204 offset:3072
	ds_read_b128 v[148:151], v204 offset:16384
	ds_read_b128 v[152:155], v204 offset:17408
	ds_read_b128 v[156:159], v204 offset:18432
	ds_read_b128 v[160:163], v204 offset:19456
	v_lshl_add_u64 v[194:195], s[8:9], 0, v[178:179]
	s_add_i32 m0, s42, 0xc000
	ds_read_b128 v[164:167], v205
	ds_read_b128 v[182:185], v205 offset:1024
	ds_read_b128 v[186:189], v205 offset:2048
	ds_read_b128 v[190:193], v205 offset:3072
	ds_read_b128 v[208:211], v205 offset:4096
	ds_read_b128 v[212:215], v205 offset:5120
	ds_read_b128 v[216:219], v205 offset:6144
	ds_read_b128 v[220:223], v205 offset:7168
	global_load_lds_dwordx4 v[194:195], off
	s_add_i32 m0, s42, 0xe000
	v_lshl_add_u64 v[194:195], s[8:9], 0, v[180:181]
	global_load_lds_dwordx4 v[194:195], off
	s_waitcnt vmcnt(8) lgkmcnt(0)
	s_barrier
	s_setprio 1
	v_mfma_f32_16x16x32_bf16 v[128:131], v[132:135], v[164:167], 0
	v_mfma_f32_16x16x32_bf16 v[124:127], v[140:143], v[164:167], 0
	v_mfma_f32_16x16x32_bf16 v[112:115], v[132:135], v[186:189], 0
	v_mfma_f32_16x16x32_bf16 v[108:111], v[140:143], v[186:189], 0
	v_mfma_f32_16x16x32_bf16 v[96:99], v[132:135], v[208:211], 0
	v_mfma_f32_16x16x32_bf16 v[92:95], v[140:143], v[208:211], 0
	v_mfma_f32_16x16x32_bf16 v[80:83], v[132:135], v[216:219], 0
	v_mfma_f32_16x16x32_bf16 v[76:79], v[140:143], v[216:219], 0
	v_mfma_f32_16x16x32_bf16 v[128:131], v[136:139], v[182:185], v[128:131]
	v_mfma_f32_16x16x32_bf16 v[124:127], v[144:147], v[182:185], v[124:127]
	v_mfma_f32_16x16x32_bf16 v[112:115], v[136:139], v[190:193], v[112:115]
	v_mfma_f32_16x16x32_bf16 v[108:111], v[144:147], v[190:193], v[108:111]
	v_mfma_f32_16x16x32_bf16 v[96:99], v[136:139], v[212:215], v[96:99]
	v_mfma_f32_16x16x32_bf16 v[92:95], v[144:147], v[212:215], v[92:95]
	v_mfma_f32_16x16x32_bf16 v[80:83], v[136:139], v[220:223], v[80:83]
	v_mfma_f32_16x16x32_bf16 v[76:79], v[144:147], v[220:223], v[76:79]
	s_setprio 0
	s_setprio 1
	v_mfma_f32_16x16x32_bf16 v[120:123], v[148:151], v[164:167], 0
	v_mfma_f32_16x16x32_bf16 v[116:119], v[156:159], v[164:167], 0
	v_mfma_f32_16x16x32_bf16 v[104:107], v[148:151], v[186:189], 0
	v_mfma_f32_16x16x32_bf16 v[100:103], v[156:159], v[186:189], 0
	v_mfma_f32_16x16x32_bf16 v[88:91], v[148:151], v[208:211], 0
	v_mfma_f32_16x16x32_bf16 v[84:87], v[156:159], v[208:211], 0
	v_mfma_f32_16x16x32_bf16 v[72:75], v[148:151], v[216:219], 0
	v_mfma_f32_16x16x32_bf16 v[68:71], v[156:159], v[216:219], 0
	v_mfma_f32_16x16x32_bf16 v[120:123], v[152:155], v[182:185], v[120:123]
	v_mfma_f32_16x16x32_bf16 v[116:119], v[160:163], v[182:185], v[116:119]
	v_mfma_f32_16x16x32_bf16 v[104:107], v[152:155], v[190:193], v[104:107]
	v_mfma_f32_16x16x32_bf16 v[100:103], v[160:163], v[190:193], v[100:103]
	v_mfma_f32_16x16x32_bf16 v[88:91], v[152:155], v[212:215], v[88:91]
	v_mfma_f32_16x16x32_bf16 v[84:87], v[160:163], v[212:215], v[84:87]
	v_mfma_f32_16x16x32_bf16 v[72:75], v[152:155], v[220:223], v[72:75]
	v_mfma_f32_16x16x32_bf16 v[68:71], v[160:163], v[220:223], v[68:71]
	s_setprio 0
	s_barrier
	v_lshl_add_u64 v[194:195], s[28:29], 0, v[168:169]
	s_add_i32 m0, s41, 0x10000
	ds_read_b128 v[164:167], v205 offset:16384
	ds_read_b128 v[182:185], v205 offset:17408
	ds_read_b128 v[186:189], v205 offset:18432
	ds_read_b128 v[190:193], v205 offset:19456
	ds_read_b128 v[208:211], v205 offset:20480
	ds_read_b128 v[212:215], v205 offset:21504
	ds_read_b128 v[216:219], v205 offset:22528
	ds_read_b128 v[220:223], v205 offset:23552
	global_load_lds_dwordx4 v[194:195], off
	s_add_i32 m0, s41, 0x12000
	s_add_u32 s54, s28, 0x40000
	v_lshl_add_u64 v[202:203], s[28:29], 0, v[172:173]
	s_addc_u32 s55, s29, 0
	global_load_lds_dwordx4 v[202:203], off
	v_lshl_add_u64 v[244:245], s[54:55], 0, v[168:169]
	s_add_i32 m0, s41, 0x14000
	v_lshl_add_u64 v[226:227], s[30:31], 0, v[170:171]
	global_load_lds_dwordx4 v[244:245], off
	s_add_i32 m0, s41, 0x16000
	v_lshl_add_u64 v[246:247], s[54:55], 0, v[172:173]
	global_load_lds_dwordx4 v[246:247], off
	v_lshl_add_u64 v[224:225], s[30:31], 0, v[0:1]
	s_waitcnt vmcnt(6) lgkmcnt(0)
	s_barrier
; #define PG8_STAGE(bufoff, gbase, voff) do { _Pragma("unroll") for (int _i = 0; _i < 2; ++_i) \
;         __builtin_amdgcn_global_load_lds((const unsigned*)((const char*)(gbase) + (voff)[_i]), (PG8_LAS unsigned*)(lds + (bufoff) + ldsw + _i * 8192), 16, 0, 0); } while (0)
; #define PG8_LDA(dst, b, h) do { _Pragma("unroll") for (int m = 0; m < 4; ++m) _Pragma("unroll") for (int k = 0; k < 2; ++k) dst[m][k] = *(const PG8_LAS bf16x8*)(lds + PG8_SA(b, h) + aoff + m * 2048 + k * 1024); } while (0)
; #define PG8_LDB(dst, b, h) do { _Pragma("unroll") for (int n = 0; n < 2; ++n) _Pragma("unroll") for (int k = 0; k < 2; ++k) dst[n][k] = *(const PG8_LAS bf16x8*)(lds + PG8_SB(b, h) + boff + n * 2048 + k * 1024); } while (0)
; #define PG8_MMA(ai, bj, At, Bt) do { __builtin_amdgcn_s_setprio(1); _Pragma("unroll") for (int m = 0; m < 4; ++m) _Pragma("unroll") for (int n = 0; n < 2; ++n) _Pragma("unroll") for (int k = 0; k < 2; ++k) \
;         acc[ai][bj][m][n] = __builtin_amdgcn_mfma_f32_16x16x32_bf16(Bt[n][k], At[m][k], acc[ai][bj][m][n], 0, 0, 0); __builtin_amdgcn_s_setprio(0); } while (0)
; #define PG8_WAIT_V(n) asm volatile("s_waitcnt vmcnt(" #n ")" ::: "memory")
; #define PG8_WAIT_L(n) asm volatile("s_waitcnt lgkmcnt(" #n ")" ::: "memory")
; #define PG8_BAR __builtin_amdgcn_s_barrier()
; #define PG8_SCHED __builtin_amdgcn_sched_barrier(0)
; template <class Epi, class Sched, bool ALIGN_EPI = false, bool SP2 = false>
; __device__ __forceinline__ void gemm_phase(PG8_LAS unsigned char* lds, const Gemm g, const Sched& S, const Epi& E) {
;     ...
;             const bool last = (t == nt - 2);
;             const char* a1 = cA + (size_t)(t + 1) * kstep;
;             const char* a2 = last ? nA : cA + (size_t)(t + 2) * kstep; const char* b2 = last ? nB : cB + (size_t)(t + 2) * kstep;
;             const char* a3 = a2 + kstep; const char* b3 = b2 + kstep;
;             if (last && has_next) S.a_ready(nxt);
;             if constexpr (SP2) {
;             PG8_LDB(B0, 0, 0); PG8_LDB(B1, 0, 1); PG8_SCHED; PG8_LDA(At, 0, 0); PG8_STAGE(PG8_SA(1, 1), a1 + hstep, voffA);
;             PG8_WAIT_V(8); PG8_WAIT_L(0); PG8_BAR; PG8_MMA(0, 0, At, B0); PG8_MMA(0, 1, At, B1); PG8_BAR; PG8_SCHED;
;     ...
;             PG8_WAIT_V(8); PG8_WAIT_L(0); PG8_BAR; PG8_MMA(1, 0, At, B0); PG8_MMA(1, 1, At, B1); PG8_BAR; PG8_SCHED;
	s_setprio 1
	v_mfma_f32_16x16x32_bf16 v[64:67], v[132:135], v[164:167], 0
	v_mfma_f32_16x16x32_bf16 v[60:63], v[140:143], v[164:167], 0
	v_mfma_f32_16x16x32_bf16 v[48:51], v[132:135], v[186:189], 0
	v_mfma_f32_16x16x32_bf16 v[44:47], v[140:143], v[186:189], 0
	v_mfma_f32_16x16x32_bf16 v[32:35], v[132:135], v[208:211], 0
	v_mfma_f32_16x16x32_bf16 v[28:31], v[140:143], v[208:211], 0
	v_mfma_f32_16x16x32_bf16 v[16:19], v[132:135], v[216:219], 0
	v_mfma_f32_16x16x32_bf16 v[12:15], v[140:143], v[216:219], 0
	v_mfma_f32_16x16x32_bf16 v[64:67], v[136:139], v[182:185], v[64:67]
	v_mfma_f32_16x16x32_bf16 v[60:63], v[144:147], v[182:185], v[60:63]
	v_mfma_f32_16x16x32_bf16 v[48:51], v[136:139], v[190:193], v[48:51]
	v_mfma_f32_16x16x32_bf16 v[44:47], v[144:147], v[190:193], v[44:47]
	v_mfma_f32_16x16x32_bf16 v[32:35], v[136:139], v[212:215], v[32:35]
	v_mfma_f32_16x16x32_bf16 v[28:31], v[144:147], v[212:215], v[28:31]
	v_mfma_f32_16x16x32_bf16 v[16:19], v[136:139], v[220:223], v[16:19]
	v_mfma_f32_16x16x32_bf16 v[12:15], v[144:147], v[220:223], v[12:15]
	s_setprio 0
	s_setprio 1
	v_mfma_f32_16x16x32_bf16 v[56:59], v[148:151], v[164:167], 0
	v_mfma_f32_16x16x32_bf16 v[52:55], v[156:159], v[164:167], 0
	v_mfma_f32_16x16x32_bf16 v[40:43], v[148:151], v[186:189], 0
	v_mfma_f32_16x16x32_bf16 v[36:39], v[156:159], v[186:189], 0
	v_mfma_f32_16x16x32_bf16 v[24:27], v[148:151], v[208:211], 0
	v_mfma_f32_16x16x32_bf16 v[20:23], v[156:159], v[208:211], 0
	v_mfma_f32_16x16x32_bf16 v[8:11], v[148:151], v[216:219], 0
	v_mfma_f32_16x16x32_bf16 v[4:7], v[156:159], v[216:219], 0
	v_mfma_f32_16x16x32_bf16 v[56:59], v[152:155], v[182:185], v[56:59]
	v_mfma_f32_16x16x32_bf16 v[52:55], v[160:163], v[182:185], v[52:55]
	v_mfma_f32_16x16x32_bf16 v[40:43], v[152:155], v[190:193], v[40:43]
	v_mfma_f32_16x16x32_bf16 v[36:39], v[160:163], v[190:193], v[36:39]
	v_mfma_f32_16x16x32_bf16 v[24:27], v[152:155], v[212:215], v[24:27]
	v_mfma_f32_16x16x32_bf16 v[20:23], v[160:163], v[212:215], v[20:23]
	v_mfma_f32_16x16x32_bf16 v[8:11], v[152:155], v[220:223], v[8:11]
	v_mfma_f32_16x16x32_bf16 v[4:7], v[160:163], v[220:223], v[4:7]
	s_setprio 0
	s_barrier
	s_branch .Lkmid_0
.LBB0_100:
	s_add_u32 s28, s8, 0xfffc0080
	s_addc_u32 s29, s9, -1
	s_cmp_eq_u32 s45, 12
	s_cselect_b32 s31, s3, s29
	s_cselect_b32 s30, s7, s28
	s_cselect_b32 s29, s11, s44
	s_cselect_b32 s28, s21, s23
	s_add_i32 m0, s50, 0xffffff80
	ds_read_b128 v[132:135], v204
	ds_read_b128 v[136:139], v204 offset:1024
	ds_read_b128 v[140:143], v204 offset:2048
	ds_read_b128 v[144:147], v204 offset:3072
	ds_read_b128 v[148:151], v204 offset:16384
	ds_read_b128 v[152:155], v204 offset:17408
	ds_read_b128 v[156:159], v204 offset:18432
	ds_read_b128 v[160:163], v204 offset:19456
	global_load_lds_dwordx4 v[224:225], off offset:128
	s_add_i32 m0, s51, 0xffffff80
	v_lshl_add_u64 v[194:195], s[8:9], 0, v[178:179]
	global_load_lds_dwordx4 v[226:227], off offset:128
	s_add_i32 m0, s42, 0xc000
	ds_read_b128 v[164:167], v205
	ds_read_b128 v[182:185], v205 offset:1024
	ds_read_b128 v[186:189], v205 offset:2048
	ds_read_b128 v[190:193], v205 offset:3072
	ds_read_b128 v[208:211], v205 offset:4096
	ds_read_b128 v[212:215], v205 offset:5120
	ds_read_b128 v[216:219], v205 offset:6144
	ds_read_b128 v[220:223], v205 offset:7168
	global_load_lds_dwordx4 v[194:195], off
	s_add_i32 m0, s42, 0xe000
	v_lshl_add_u64 v[194:195], s[8:9], 0, v[180:181]
	global_load_lds_dwordx4 v[194:195], off
	s_waitcnt vmcnt(8) lgkmcnt(0)
	s_barrier
	s_setprio 1
	v_mfma_f32_16x16x32_bf16 v[128:131], v[132:135], v[164:167], v[128:131]
	v_mfma_f32_16x16x32_bf16 v[124:127], v[140:143], v[164:167], v[124:127]
	v_mfma_f32_16x16x32_bf16 v[112:115], v[132:135], v[186:189], v[112:115]
	v_mfma_f32_16x16x32_bf16 v[108:111], v[140:143], v[186:189], v[108:111]
	v_mfma_f32_16x16x32_bf16 v[96:99], v[132:135], v[208:211], v[96:99]
	v_mfma_f32_16x16x32_bf16 v[92:95], v[140:143], v[208:211], v[92:95]
	v_mfma_f32_16x16x32_bf16 v[80:83], v[132:135], v[216:219], v[80:83]
	v_mfma_f32_16x16x32_bf16 v[76:79], v[140:143], v[216:219], v[76:79]
	v_mfma_f32_16x16x32_bf16 v[128:131], v[136:139], v[182:185], v[128:131]
	v_mfma_f32_16x16x32_bf16 v[124:127], v[144:147], v[182:185], v[124:127]
	v_mfma_f32_16x16x32_bf16 v[112:115], v[136:139], v[190:193], v[112:115]
	v_mfma_f32_16x16x32_bf16 v[108:111], v[144:147], v[190:193], v[108:111]
	v_mfma_f32_16x16x32_bf16 v[96:99], v[136:139], v[212:215], v[96:99]
	v_mfma_f32_16x16x32_bf16 v[92:95], v[144:147], v[212:215], v[92:95]
	v_mfma_f32_16x16x32_bf16 v[80:83], v[136:139], v[220:223], v[80:83]
	v_mfma_f32_16x16x32_bf16 v[76:79], v[144:147], v[220:223], v[76:79]
	s_setprio 0
	s_setprio 1
	v_mfma_f32_16x16x32_bf16 v[120:123], v[148:151], v[164:167], v[120:123]
	v_mfma_f32_16x16x32_bf16 v[116:119], v[156:159], v[164:167], v[116:119]
	v_mfma_f32_16x16x32_bf16 v[104:107], v[148:151], v[186:189], v[104:107]
	v_mfma_f32_16x16x32_bf16 v[100:103], v[156:159], v[186:189], v[100:103]
	v_mfma_f32_16x16x32_bf16 v[88:91], v[148:151], v[208:211], v[88:91]
	v_mfma_f32_16x16x32_bf16 v[84:87], v[156:159], v[208:211], v[84:87]
	v_mfma_f32_16x16x32_bf16 v[72:75], v[148:151], v[216:219], v[72:75]
	v_mfma_f32_16x16x32_bf16 v[68:71], v[156:159], v[216:219], v[68:71]
	v_mfma_f32_16x16x32_bf16 v[120:123], v[152:155], v[182:185], v[120:123]
	v_mfma_f32_16x16x32_bf16 v[116:119], v[160:163], v[182:185], v[116:119]
	v_mfma_f32_16x16x32_bf16 v[104:107], v[152:155], v[190:193], v[104:107]
	v_mfma_f32_16x16x32_bf16 v[100:103], v[160:163], v[190:193], v[100:103]
	v_mfma_f32_16x16x32_bf16 v[88:91], v[152:155], v[212:215], v[88:91]
	v_mfma_f32_16x16x32_bf16 v[84:87], v[160:163], v[212:215], v[84:87]
	v_mfma_f32_16x16x32_bf16 v[72:75], v[152:155], v[220:223], v[72:75]
	v_mfma_f32_16x16x32_bf16 v[68:71], v[160:163], v[220:223], v[68:71]
	s_setprio 0
	s_barrier
; #define PG8_STAGE(bufoff, gbase, voff) do { _Pragma("unroll") for (int _i = 0; _i < 2; ++_i) \
;         __builtin_amdgcn_global_load_lds((const unsigned*)((const char*)(gbase) + (voff)[_i]), (PG8_LAS unsigned*)(lds + (bufoff) + ldsw + _i * 8192), 16, 0, 0); } while (0)
; #define PG8_LDA(dst, b, h) do { _Pragma("unroll") for (int m = 0; m < 4; ++m) _Pragma("unroll") for (int k = 0; k < 2; ++k) dst[m][k] = *(const PG8_LAS bf16x8*)(lds + PG8_SA(b, h) + aoff + m * 2048 + k * 1024); } while (0)
; #define PG8_MMA(ai, bj, At, Bt) do { __builtin_amdgcn_s_setprio(1); _Pragma("unroll") for (int m = 0; m < 4; ++m) _Pragma("unroll") for (int n = 0; n < 2; ++n) _Pragma("unroll") for (int k = 0; k < 2; ++k) \
;         acc[ai][bj][m][n] = __builtin_amdgcn_mfma_f32_16x16x32_bf16(Bt[n][k], At[m][k], acc[ai][bj][m][n], 0, 0, 0); __builtin_amdgcn_s_setprio(0); } while (0)
; #define PG8_WAIT_V(n) asm volatile("s_waitcnt vmcnt(" #n ")" ::: "memory")
; #define PG8_WAIT_L(n) asm volatile("s_waitcnt lgkmcnt(" #n ")" ::: "memory")
; #define PG8_BAR __builtin_amdgcn_s_barrier()
; #define PG8_SCHED __builtin_amdgcn_sched_barrier(0)
; template <class Epi, class Sched, bool ALIGN_EPI = false, bool SP2 = false>
; __device__ __forceinline__ void gemm_phase(PG8_LAS unsigned char* lds, const Gemm g, const Sched& S, const Epi& E) {
;     ...
;             PG8_LDA(At, 0, 1); PG8_STAGE(PG8_SB(0, 0), b2, voffB); PG8_STAGE(PG8_SB(0, 1), b2 + hstep, voffB); PG8_STAGE(PG8_SA(0, 0), a2, voffA);
;             PG8_WAIT_V(8); PG8_WAIT_L(0); PG8_BAR; PG8_MMA(1, 0, At, B0); PG8_MMA(1, 1, At, B1); PG8_BAR; PG8_SCHED;
	v_lshl_add_u64 v[194:195], s[28:29], 0, v[168:169]
	s_add_i32 m0, s41, 0x10000
	ds_read_b128 v[164:167], v205 offset:16384
	ds_read_b128 v[182:185], v205 offset:17408
	ds_read_b128 v[186:189], v205 offset:18432
	ds_read_b128 v[190:193], v205 offset:19456
	ds_read_b128 v[208:211], v205 offset:20480
	ds_read_b128 v[212:215], v205 offset:21504
	ds_read_b128 v[216:219], v205 offset:22528
	ds_read_b128 v[220:223], v205 offset:23552
	global_load_lds_dwordx4 v[194:195], off
	s_add_i32 m0, s41, 0x12000
	s_add_u32 s54, s28, 0x40000
	v_lshl_add_u64 v[202:203], s[28:29], 0, v[172:173]
	s_addc_u32 s55, s29, 0
	global_load_lds_dwordx4 v[202:203], off
	v_lshl_add_u64 v[244:245], s[54:55], 0, v[168:169]
	s_add_i32 m0, s41, 0x14000
	v_lshl_add_u64 v[226:227], s[30:31], 0, v[170:171]
	global_load_lds_dwordx4 v[244:245], off
	s_add_i32 m0, s41, 0x16000
	v_lshl_add_u64 v[246:247], s[54:55], 0, v[172:173]
	global_load_lds_dwordx4 v[246:247], off
	v_lshl_add_u64 v[224:225], s[30:31], 0, v[0:1]
	s_waitcnt vmcnt(6) lgkmcnt(0)
	s_barrier
	s_setprio 1
	v_mfma_f32_16x16x32_bf16 v[64:67], v[132:135], v[164:167], v[64:67]
	v_mfma_f32_16x16x32_bf16 v[60:63], v[140:143], v[164:167], v[60:63]
	v_mfma_f32_16x16x32_bf16 v[48:51], v[132:135], v[186:189], v[48:51]
	v_mfma_f32_16x16x32_bf16 v[44:47], v[140:143], v[186:189], v[44:47]
	v_mfma_f32_16x16x32_bf16 v[32:35], v[132:135], v[208:211], v[32:35]
	v_mfma_f32_16x16x32_bf16 v[28:31], v[140:143], v[208:211], v[28:31]
	v_mfma_f32_16x16x32_bf16 v[16:19], v[132:135], v[216:219], v[16:19]
	v_mfma_f32_16x16x32_bf16 v[12:15], v[140:143], v[216:219], v[12:15]
	v_mfma_f32_16x16x32_bf16 v[64:67], v[136:139], v[182:185], v[64:67]
	v_mfma_f32_16x16x32_bf16 v[60:63], v[144:147], v[182:185], v[60:63]
	v_mfma_f32_16x16x32_bf16 v[48:51], v[136:139], v[190:193], v[48:51]
	v_mfma_f32_16x16x32_bf16 v[44:47], v[144:147], v[190:193], v[44:47]
	v_mfma_f32_16x16x32_bf16 v[32:35], v[136:139], v[212:215], v[32:35]
	v_mfma_f32_16x16x32_bf16 v[28:31], v[144:147], v[212:215], v[28:31]
	v_mfma_f32_16x16x32_bf16 v[16:19], v[136:139], v[220:223], v[16:19]
	v_mfma_f32_16x16x32_bf16 v[12:15], v[144:147], v[220:223], v[12:15]
	s_setprio 0
	s_setprio 1
	v_mfma_f32_16x16x32_bf16 v[56:59], v[148:151], v[164:167], v[56:59]
	v_mfma_f32_16x16x32_bf16 v[52:55], v[156:159], v[164:167], v[52:55]
	v_mfma_f32_16x16x32_bf16 v[40:43], v[148:151], v[186:189], v[40:43]
	v_mfma_f32_16x16x32_bf16 v[36:39], v[156:159], v[186:189], v[36:39]
	v_mfma_f32_16x16x32_bf16 v[24:27], v[148:151], v[208:211], v[24:27]
	v_mfma_f32_16x16x32_bf16 v[20:23], v[156:159], v[208:211], v[20:23]
	v_mfma_f32_16x16x32_bf16 v[8:11], v[148:151], v[216:219], v[8:11]
	v_mfma_f32_16x16x32_bf16 v[4:7], v[156:159], v[216:219], v[4:7]
	v_mfma_f32_16x16x32_bf16 v[56:59], v[152:155], v[182:185], v[56:59]
	v_mfma_f32_16x16x32_bf16 v[52:55], v[160:163], v[182:185], v[52:55]
	v_mfma_f32_16x16x32_bf16 v[40:43], v[152:155], v[190:193], v[40:43]
	v_mfma_f32_16x16x32_bf16 v[36:39], v[160:163], v[190:193], v[36:39]
	v_mfma_f32_16x16x32_bf16 v[24:27], v[152:155], v[212:215], v[24:27]
	v_mfma_f32_16x16x32_bf16 v[20:23], v[160:163], v[212:215], v[20:23]
	v_mfma_f32_16x16x32_bf16 v[8:11], v[152:155], v[220:223], v[8:11]
	v_mfma_f32_16x16x32_bf16 v[4:7], v[160:163], v[220:223], v[4:7]
	s_setprio 0
	s_barrier
; #define PG8_STAGE(bufoff, gbase, voff) do { _Pragma("unroll") for (int _i = 0; _i < 2; ++_i) \
;         __builtin_amdgcn_global_load_lds((const unsigned*)((const char*)(gbase) + (voff)[_i]), (PG8_LAS unsigned*)(lds + (bufoff) + ldsw + _i * 8192), 16, 0, 0); } while (0)
; #define PG8_LDA(dst, b, h) do { _Pragma("unroll") for (int m = 0; m < 4; ++m) _Pragma("unroll") for (int k = 0; k < 2; ++k) dst[m][k] = *(const PG8_LAS bf16x8*)(lds + PG8_SA(b, h) + aoff + m * 2048 + k * 1024); } while (0)
; #define PG8_LDB(dst, b, h) do { _Pragma("unroll") for (int n = 0; n < 2; ++n) _Pragma("unroll") for (int k = 0; k < 2; ++k) dst[n][k] = *(const PG8_LAS bf16x8*)(lds + PG8_SB(b, h) + boff + n * 2048 + k * 1024); } while (0)
; #define PG8_MMA(ai, bj, At, Bt) do { __builtin_amdgcn_s_setprio(1); _Pragma("unroll") for (int m = 0; m < 4; ++m) _Pragma("unroll") for (int n = 0; n < 2; ++n) _Pragma("unroll") for (int k = 0; k < 2; ++k) \
;         acc[ai][bj][m][n] = __builtin_amdgcn_mfma_f32_16x16x32_bf16(Bt[n][k], At[m][k], acc[ai][bj][m][n], 0, 0, 0); __builtin_amdgcn_s_setprio(0); } while (0)
; #define PG8_WAIT_V(n) asm volatile("s_waitcnt vmcnt(" #n ")" ::: "memory")
; #define PG8_WAIT_L(n) asm volatile("s_waitcnt lgkmcnt(" #n ")" ::: "memory")
; #define PG8_BAR __builtin_amdgcn_s_barrier()
; #define PG8_SCHED __builtin_amdgcn_sched_barrier(0)
; template <class Epi, class Sched, bool ALIGN_EPI = false, bool SP2 = false>
; __device__ __forceinline__ void gemm_phase(PG8_LAS unsigned char* lds, const Gemm g, const Sched& S, const Epi& E) {
;     ...
;             PG8_LDB(B0, 1, 0); PG8_LDB(B1, 1, 1); PG8_SCHED; PG8_LDA(At, 1, 0); PG8_STAGE(PG8_SA(0, 1), a2 + hstep, voffA);
;             PG8_WAIT_V(8); PG8_WAIT_L(0); PG8_BAR; PG8_MMA(0, 0, At, B0); PG8_MMA(0, 1, At, B1); PG8_BAR; PG8_SCHED;
;             PG8_LDA(At, 1, 1); PG8_STAGE(PG8_SB(1, 0), b3, voffB); PG8_STAGE(PG8_SB(1, 1), b3 + hstep, voffB); PG8_STAGE(PG8_SA(1, 0), a3, voffA);
;             PG8_WAIT_V(8); PG8_WAIT_L(0); PG8_BAR; PG8_MMA(1, 0, At, B0); PG8_MMA(1, 1, At, B1); PG8_BAR; PG8_SCHED;
.Lkmid_0:
	ds_read_b128 v[132:135], v204 offset:32768
	ds_read_b128 v[136:139], v204 offset:33792
	ds_read_b128 v[140:143], v204 offset:34816
	ds_read_b128 v[144:147], v204 offset:35840
	ds_read_b128 v[148:151], v204 offset:49152
	ds_read_b128 v[152:155], v204 offset:50176
	ds_read_b128 v[156:159], v204 offset:51200
	ds_read_b128 v[160:163], v204 offset:52224
	s_mov_b32 m0, s42
	s_add_u32 s30, s30, 0x40000
	s_addc_u32 s31, s31, 0
	global_load_lds_dwordx4 v[224:225], off
	s_mov_b32 m0, s43
	v_lshl_add_u64 v[228:229], s[30:31], 0, v[0:1]
	global_load_lds_dwordx4 v[226:227], off
	s_mov_b32 m0, s46
	ds_read_b128 v[164:167], v205 offset:32768
	ds_read_b128 v[182:185], v205 offset:33792
	ds_read_b128 v[186:189], v205 offset:34816
	ds_read_b128 v[190:193], v205 offset:35840
	ds_read_b128 v[208:211], v205 offset:36864
	ds_read_b128 v[212:215], v205 offset:37888
	ds_read_b128 v[216:219], v205 offset:38912
	ds_read_b128 v[220:223], v205 offset:39936
	global_load_lds_dwordx4 v[228:229], off
	s_mov_b32 m0, s47
	v_lshl_add_u64 v[228:229], s[30:31], 0, v[170:171]
	global_load_lds_dwordx4 v[228:229], off
	s_waitcnt vmcnt(8) lgkmcnt(0)
	s_barrier
	s_setprio 1
	v_mfma_f32_16x16x32_bf16 v[128:131], v[132:135], v[164:167], v[128:131]
	v_mfma_f32_16x16x32_bf16 v[124:127], v[140:143], v[164:167], v[124:127]
	v_mfma_f32_16x16x32_bf16 v[112:115], v[132:135], v[186:189], v[112:115]
	v_mfma_f32_16x16x32_bf16 v[108:111], v[140:143], v[186:189], v[108:111]
	v_mfma_f32_16x16x32_bf16 v[96:99], v[132:135], v[208:211], v[96:99]
	v_mfma_f32_16x16x32_bf16 v[92:95], v[140:143], v[208:211], v[92:95]
	v_mfma_f32_16x16x32_bf16 v[80:83], v[132:135], v[216:219], v[80:83]
	v_mfma_f32_16x16x32_bf16 v[76:79], v[140:143], v[216:219], v[76:79]
	v_mfma_f32_16x16x32_bf16 v[128:131], v[136:139], v[182:185], v[128:131]
	v_mfma_f32_16x16x32_bf16 v[124:127], v[144:147], v[182:185], v[124:127]
	v_mfma_f32_16x16x32_bf16 v[112:115], v[136:139], v[190:193], v[112:115]
	v_mfma_f32_16x16x32_bf16 v[108:111], v[144:147], v[190:193], v[108:111]
	v_mfma_f32_16x16x32_bf16 v[96:99], v[136:139], v[212:215], v[96:99]
	v_mfma_f32_16x16x32_bf16 v[92:95], v[144:147], v[212:215], v[92:95]
	v_mfma_f32_16x16x32_bf16 v[80:83], v[136:139], v[220:223], v[80:83]
	v_mfma_f32_16x16x32_bf16 v[76:79], v[144:147], v[220:223], v[76:79]
	s_setprio 0
	s_setprio 1
	v_mfma_f32_16x16x32_bf16 v[120:123], v[148:151], v[164:167], v[120:123]
	v_mfma_f32_16x16x32_bf16 v[116:119], v[156:159], v[164:167], v[116:119]
	v_mfma_f32_16x16x32_bf16 v[104:107], v[148:151], v[186:189], v[104:107]
	v_mfma_f32_16x16x32_bf16 v[100:103], v[156:159], v[186:189], v[100:103]
	v_mfma_f32_16x16x32_bf16 v[88:91], v[148:151], v[208:211], v[88:91]
	v_mfma_f32_16x16x32_bf16 v[84:87], v[156:159], v[208:211], v[84:87]
	v_mfma_f32_16x16x32_bf16 v[72:75], v[148:151], v[216:219], v[72:75]
	v_mfma_f32_16x16x32_bf16 v[68:71], v[156:159], v[216:219], v[68:71]
	v_mfma_f32_16x16x32_bf16 v[120:123], v[152:155], v[182:185], v[120:123]
	v_mfma_f32_16x16x32_bf16 v[116:119], v[160:163], v[182:185], v[116:119]
	v_mfma_f32_16x16x32_bf16 v[104:107], v[152:155], v[190:193], v[104:107]
	v_mfma_f32_16x16x32_bf16 v[100:103], v[160:163], v[190:193], v[100:103]
	v_mfma_f32_16x16x32_bf16 v[88:91], v[152:155], v[212:215], v[88:91]
	v_mfma_f32_16x16x32_bf16 v[84:87], v[160:163], v[212:215], v[84:87]
	v_mfma_f32_16x16x32_bf16 v[72:75], v[152:155], v[220:223], v[72:75]
	v_mfma_f32_16x16x32_bf16 v[68:71], v[160:163], v[220:223], v[68:71]
	s_setprio 0
	s_barrier
	s_add_i32 m0, s41, 0x17f80
	ds_read_b128 v[164:167], v205 offset:49152
	ds_read_b128 v[182:185], v205 offset:50176
	ds_read_b128 v[186:189], v205 offset:51200
	ds_read_b128 v[190:193], v205 offset:52224
	ds_read_b128 v[208:211], v205 offset:53248
	ds_read_b128 v[212:215], v205 offset:54272
	ds_read_b128 v[216:219], v205 offset:55296
	ds_read_b128 v[220:223], v205 offset:56320
	global_load_lds_dwordx4 v[194:195], off offset:128
	s_add_i32 m0, s41, 0x19f80
	s_add_u32 s8, s8, 0x100
	s_addc_u32 s9, s9, 0
	global_load_lds_dwordx4 v[202:203], off offset:128
	s_add_i32 m0, s41, 0x1bf80
	s_add_u32 s23, s23, 0x100
	s_addc_u32 s44, s44, 0
	global_load_lds_dwordx4 v[244:245], off offset:128
	s_add_i32 m0, s41, 0x1df80
	s_cmp_eq_u32 s45, 12
	global_load_lds_dwordx4 v[246:247], off offset:128
	s_cbranch_scc0 .Lks4_0
	s_add_i32 m0, s50, 0xffffff80
	s_nop 0
	global_load_lds_dwordx4 v[224:225], off offset:128
	s_add_i32 m0, s51, 0xffffff80
	s_nop 0
	global_load_lds_dwordx4 v[226:227], off offset:128
.Lks4_0:
	s_waitcnt vmcnt(6) lgkmcnt(0)
	s_barrier
	s_setprio 1
	v_mfma_f32_16x16x32_bf16 v[64:67], v[132:135], v[164:167], v[64:67]
	v_mfma_f32_16x16x32_bf16 v[60:63], v[140:143], v[164:167], v[60:63]
	v_mfma_f32_16x16x32_bf16 v[48:51], v[132:135], v[186:189], v[48:51]
	v_mfma_f32_16x16x32_bf16 v[44:47], v[140:143], v[186:189], v[44:47]
	v_mfma_f32_16x16x32_bf16 v[32:35], v[132:135], v[208:211], v[32:35]
	v_mfma_f32_16x16x32_bf16 v[28:31], v[140:143], v[208:211], v[28:31]
	v_mfma_f32_16x16x32_bf16 v[16:19], v[132:135], v[216:219], v[16:19]
	v_mfma_f32_16x16x32_bf16 v[12:15], v[140:143], v[216:219], v[12:15]
	v_mfma_f32_16x16x32_bf16 v[64:67], v[136:139], v[182:185], v[64:67]
	v_mfma_f32_16x16x32_bf16 v[60:63], v[144:147], v[182:185], v[60:63]
	v_mfma_f32_16x16x32_bf16 v[48:51], v[136:139], v[190:193], v[48:51]
	v_mfma_f32_16x16x32_bf16 v[44:47], v[144:147], v[190:193], v[44:47]
	v_mfma_f32_16x16x32_bf16 v[32:35], v[136:139], v[212:215], v[32:35]
	v_mfma_f32_16x16x32_bf16 v[28:31], v[144:147], v[212:215], v[28:31]
	v_mfma_f32_16x16x32_bf16 v[16:19], v[136:139], v[220:223], v[16:19]
	v_mfma_f32_16x16x32_bf16 v[12:15], v[144:147], v[220:223], v[12:15]
	s_setprio 0
	s_setprio 1
	v_mfma_f32_16x16x32_bf16 v[56:59], v[148:151], v[164:167], v[56:59]
	v_mfma_f32_16x16x32_bf16 v[52:55], v[156:159], v[164:167], v[52:55]
	v_mfma_f32_16x16x32_bf16 v[40:43], v[148:151], v[186:189], v[40:43]
	v_mfma_f32_16x16x32_bf16 v[36:39], v[156:159], v[186:189], v[36:39]
	v_mfma_f32_16x16x32_bf16 v[24:27], v[148:151], v[208:211], v[24:27]
	v_mfma_f32_16x16x32_bf16 v[20:23], v[156:159], v[208:211], v[20:23]
	v_mfma_f32_16x16x32_bf16 v[8:11], v[148:151], v[216:219], v[8:11]
	v_mfma_f32_16x16x32_bf16 v[4:7], v[156:159], v[216:219], v[4:7]
	v_mfma_f32_16x16x32_bf16 v[56:59], v[152:155], v[182:185], v[56:59]
	v_mfma_f32_16x16x32_bf16 v[52:55], v[160:163], v[182:185], v[52:55]
	v_mfma_f32_16x16x32_bf16 v[40:43], v[152:155], v[190:193], v[40:43]
	v_mfma_f32_16x16x32_bf16 v[36:39], v[160:163], v[190:193], v[36:39]
	v_mfma_f32_16x16x32_bf16 v[24:27], v[152:155], v[212:215], v[24:27]
	v_mfma_f32_16x16x32_bf16 v[20:23], v[160:163], v[212:215], v[20:23]
	v_mfma_f32_16x16x32_bf16 v[8:11], v[152:155], v[220:223], v[8:11]
	v_mfma_f32_16x16x32_bf16 v[4:7], v[160:163], v[220:223], v[4:7]
	s_setprio 0
	s_barrier
	s_add_i32 s45, s45, 2
	s_cmp_gt_u32 s45, 13
	s_cbranch_scc0 .LBB0_100
	s_and_b64 vcc, exec, s[14:15]
	s_cbranch_vccz .LBB0_103
	s_barrier

; #define PG8_STAGE(bufoff, gbase, voff) do { _Pragma("unroll") for (int _i = 0; _i < 2; ++_i) \
;         __builtin_amdgcn_global_load_lds((const unsigned*)((const char*)(gbase) + (voff)[_i]), (PG8_LAS unsigned*)(lds + (bufoff) + ldsw + _i * 8192), 16, 0, 0); } while (0)
; #define PG8_LDA(dst, b, h) do { _Pragma("unroll") for (int m = 0; m < 4; ++m) _Pragma("unroll") for (int k = 0; k < 2; ++k) dst[m][k] = *(const PG8_LAS bf16x8*)(lds + PG8_SA(b, h) + aoff + m * 2048 + k * 1024); } while (0)
; #define PG8_LDB(dst, b, h) do { _Pragma("unroll") for (int n = 0; n < 2; ++n) _Pragma("unroll") for (int k = 0; k < 2; ++k) dst[n][k] = *(const PG8_LAS bf16x8*)(lds + PG8_SB(b, h) + boff + n * 2048 + k * 1024); } while (0)
; #define PG8_WAIT_V(n) asm volatile("s_waitcnt vmcnt(" #n ")" ::: "memory")
; #define PG8_WAIT_L(n) asm volatile("s_waitcnt lgkmcnt(" #n ")" ::: "memory")
; #define PG8_BAR __builtin_amdgcn_s_barrier()
; #define PG8_SCHED __builtin_amdgcn_sched_barrier(0)
; template <class Epi, class Sched, bool ALIGN_EPI = false, bool SP2 = false>
; __device__ __forceinline__ void gemm_phase(PG8_LAS unsigned char* lds, const Gemm g, const Sched& S, const Epi& E) {
;     ...
;         const bool has_next = S.next(ui + 1, nxt);
;         const char* nA = has_next ? (const char*)g.A + (size_t)nxt.pm * tstep : cA; const char* nB = has_next ? (const char*)g.Bt + (size_t)nxt.pn * tstep : cB;
;         for (int t = 0; t < nt; t += 2) {
;             const bool last = (t == nt - 2);
;             const char* a1 = cA + (size_t)(t + 1) * kstep;
;             const char* a2 = last ? nA : cA + (size_t)(t + 2) * kstep; const char* b2 = last ? nB : cB + (size_t)(t + 2) * kstep;
;             const char* a3 = a2 + kstep; const char* b3 = b2 + kstep;
;             if (last && has_next) S.a_ready(nxt);
;             if constexpr (SP2) {
;             PG8_LDB(B0, 0, 0); PG8_LDB(B1, 0, 1); PG8_SCHED; PG8_LDA(At, 0, 0); PG8_STAGE(PG8_SA(1, 1), a1 + hstep, voffA);
;             PG8_WAIT_V(8); PG8_WAIT_L(0); PG8_BAR; PG8_MMA(0, 0, At, B0); PG8_MMA(0, 1, At, B1); PG8_BAR; PG8_SCHED;
;             PG8_LDA(At, 0, 1); PG8_STAGE(PG8_SB(0, 0), b2, voffB); PG8_STAGE(PG8_SB(0, 1), b2 + hstep, voffB); PG8_STAGE(PG8_SA(0, 0), a2, voffA);
;             PG8_WAIT_V(8); PG8_WAIT_L(0); PG8_BAR; PG8_MMA(1, 0, At, B0); PG8_MMA(1, 1, At, B1); PG8_BAR; PG8_SCHED;
.LBB0_328:
	s_ashr_i32 s17, s16, 31
	s_lshl_b64 s[20:21], s[16:17], 19
	s_add_u32 s20, s37, s20
	s_addc_u32 s21, s38, s21
	s_and_b64 s[22:23], s[6:7], exec
	s_cselect_b32 s3, s21, s29
	s_cselect_b32 s17, s20, s28
	s_ashr_i32 s19, s18, 31
	s_lshl_b64 s[22:23], s[18:19], 19
	s_add_u32 s22, s39, s22
	s_addc_u32 s23, s40, s23
	s_and_b64 s[34:35], s[6:7], exec
	s_cselect_b32 s19, s23, s31
	s_cselect_b32 s25, s22, s30
	s_add_u32 s28, s28, 0x40080
	s_addc_u32 s29, s29, 0
	s_add_u32 s27, s30, 0x100
	s_addc_u32 s44, s31, 0
	s_mov_b32 s45, -2
	s_add_u32 s30, s28, 0xfffc0080
	s_addc_u32 s31, s29, -1
	s_cmp_eq_u32 s45, 12
	s_cselect_b32 s35, s3, s31
	s_cselect_b32 s34, s17, s30
	s_cselect_b32 s31, s19, s44
	s_cselect_b32 s30, s25, s27
	ds_read_b128 v[108:111], v251
	ds_read_b128 v[112:115], v251 offset:1024
	ds_read_b128 v[124:127], v251 offset:2048
	ds_read_b128 v[128:131], v251 offset:3072
	ds_read_b128 v[132:135], v251 offset:16384
	ds_read_b128 v[140:143], v251 offset:17408
	ds_read_b128 v[148:151], v251 offset:18432
	ds_read_b128 v[156:159], v251 offset:19456
	v_lshl_add_u64 v[212:213], s[28:29], 0, v[208:209]
	s_add_i32 m0, s42, 0xc000
	ds_read_b128 v[164:167], v253
	ds_read_b128 v[168:171], v253 offset:1024
	ds_read_b128 v[172:175], v253 offset:2048
	ds_read_b128 v[176:179], v253 offset:3072
	ds_read_b128 v[180:183], v253 offset:4096
	ds_read_b128 v[184:187], v253 offset:5120
	ds_read_b128 v[188:191], v253 offset:6144
	ds_read_b128 v[192:195], v253 offset:7168
	global_load_lds_dwordx4 v[212:213], off
	s_add_i32 m0, s42, 0xe000
	v_lshl_add_u64 v[212:213], s[28:29], 0, v[210:211]
	global_load_lds_dwordx4 v[212:213], off
	s_waitcnt vmcnt(8) lgkmcnt(0)
	s_barrier
	s_setprio 1
	v_mfma_f32_16x16x32_bf16 v[160:163], v[108:111], v[164:167], 0
	v_mfma_f32_16x16x32_bf16 v[152:155], v[124:127], v[164:167], 0
	v_mfma_f32_16x16x32_bf16 v[120:123], v[108:111], v[172:175], 0
	v_mfma_f32_16x16x32_bf16 v[116:119], v[124:127], v[172:175], 0
	v_mfma_f32_16x16x32_bf16 v[96:99], v[108:111], v[180:183], 0
	v_mfma_f32_16x16x32_bf16 v[92:95], v[124:127], v[180:183], 0
	v_mfma_f32_16x16x32_bf16 v[80:83], v[108:111], v[188:191], 0
	v_mfma_f32_16x16x32_bf16 v[76:79], v[124:127], v[188:191], 0
	v_mfma_f32_16x16x32_bf16 v[160:163], v[112:115], v[168:171], v[160:163]
	v_mfma_f32_16x16x32_bf16 v[152:155], v[128:131], v[168:171], v[152:155]
	v_mfma_f32_16x16x32_bf16 v[120:123], v[112:115], v[176:179], v[120:123]
	v_mfma_f32_16x16x32_bf16 v[116:119], v[128:131], v[176:179], v[116:119]
	v_mfma_f32_16x16x32_bf16 v[96:99], v[112:115], v[184:187], v[96:99]
	v_mfma_f32_16x16x32_bf16 v[92:95], v[128:131], v[184:187], v[92:95]
	v_mfma_f32_16x16x32_bf16 v[80:83], v[112:115], v[192:195], v[80:83]
	v_mfma_f32_16x16x32_bf16 v[76:79], v[128:131], v[192:195], v[76:79]
	s_setprio 0
	s_setprio 1
	v_mfma_f32_16x16x32_bf16 v[144:147], v[132:135], v[164:167], 0
	v_mfma_f32_16x16x32_bf16 v[136:139], v[148:151], v[164:167], 0
	v_mfma_f32_16x16x32_bf16 v[104:107], v[132:135], v[172:175], 0
	v_mfma_f32_16x16x32_bf16 v[100:103], v[148:151], v[172:175], 0
	v_mfma_f32_16x16x32_bf16 v[88:91], v[132:135], v[180:183], 0
	v_mfma_f32_16x16x32_bf16 v[84:87], v[148:151], v[180:183], 0
	v_mfma_f32_16x16x32_bf16 v[72:75], v[132:135], v[188:191], 0
	v_mfma_f32_16x16x32_bf16 v[68:71], v[148:151], v[188:191], 0
	v_mfma_f32_16x16x32_bf16 v[144:147], v[140:143], v[168:171], v[144:147]
	v_mfma_f32_16x16x32_bf16 v[136:139], v[156:159], v[168:171], v[136:139]
	v_mfma_f32_16x16x32_bf16 v[104:107], v[140:143], v[176:179], v[104:107]
	v_mfma_f32_16x16x32_bf16 v[100:103], v[156:159], v[176:179], v[100:103]
	v_mfma_f32_16x16x32_bf16 v[88:91], v[140:143], v[184:187], v[88:91]
	v_mfma_f32_16x16x32_bf16 v[84:87], v[156:159], v[184:187], v[84:87]
	v_mfma_f32_16x16x32_bf16 v[72:75], v[140:143], v[192:195], v[72:75]
	v_mfma_f32_16x16x32_bf16 v[68:71], v[156:159], v[192:195], v[68:71]
	s_setprio 0
	s_barrier
	v_lshl_add_u64 v[212:213], s[30:31], 0, v[202:203]
	s_add_i32 m0, s41, 0x10000
	ds_read_b128 v[164:167], v253 offset:16384
	ds_read_b128 v[168:171], v253 offset:17408
	ds_read_b128 v[172:175], v253 offset:18432
	ds_read_b128 v[176:179], v253 offset:19456
	ds_read_b128 v[180:183], v253 offset:20480
	ds_read_b128 v[184:187], v253 offset:21504
	ds_read_b128 v[188:191], v253 offset:22528
	ds_read_b128 v[192:195], v253 offset:23552
	global_load_lds_dwordx4 v[212:213], off
	s_add_i32 m0, s41, 0x12000
	s_add_u32 s52, s30, 0x40000
	v_lshl_add_u64 v[214:215], s[30:31], 0, v[206:207]
	s_addc_u32 s53, s31, 0
	global_load_lds_dwordx4 v[214:215], off
	v_lshl_add_u64 v[244:245], s[52:53], 0, v[202:203]
	s_add_i32 m0, s41, 0x14000
	v_lshl_add_u64 v[218:219], s[34:35], 0, v[204:205]
	global_load_lds_dwordx4 v[244:245], off
	s_add_i32 m0, s41, 0x16000
	v_lshl_add_u64 v[246:247], s[52:53], 0, v[206:207]
	global_load_lds_dwordx4 v[246:247], off
	v_lshl_add_u64 v[216:217], s[34:35], 0, v[0:1]
	s_waitcnt vmcnt(6) lgkmcnt(0)
	s_barrier
; #define PG8_STAGE(bufoff, gbase, voff) do { _Pragma("unroll") for (int _i = 0; _i < 2; ++_i) \
;         __builtin_amdgcn_global_load_lds((const unsigned*)((const char*)(gbase) + (voff)[_i]), (PG8_LAS unsigned*)(lds + (bufoff) + ldsw + _i * 8192), 16, 0, 0); } while (0)
; #define PG8_LDA(dst, b, h) do { _Pragma("unroll") for (int m = 0; m < 4; ++m) _Pragma("unroll") for (int k = 0; k < 2; ++k) dst[m][k] = *(const PG8_LAS bf16x8*)(lds + PG8_SA(b, h) + aoff + m * 2048 + k * 1024); } while (0)
; #define PG8_LDB(dst, b, h) do { _Pragma("unroll") for (int n = 0; n < 2; ++n) _Pragma("unroll") for (int k = 0; k < 2; ++k) dst[n][k] = *(const PG8_LAS bf16x8*)(lds + PG8_SB(b, h) + boff + n * 2048 + k * 1024); } while (0)
; #define PG8_MMA(ai, bj, At, Bt) do { __builtin_amdgcn_s_setprio(1); _Pragma("unroll") for (int m = 0; m < 4; ++m) _Pragma("unroll") for (int n = 0; n < 2; ++n) _Pragma("unroll") for (int k = 0; k < 2; ++k) \
;         acc[ai][bj][m][n] = __builtin_amdgcn_mfma_f32_16x16x32_bf16(Bt[n][k], At[m][k], acc[ai][bj][m][n], 0, 0, 0); __builtin_amdgcn_s_setprio(0); } while (0)
; #define PG8_WAIT_V(n) asm volatile("s_waitcnt vmcnt(" #n ")" ::: "memory")
; #define PG8_WAIT_L(n) asm volatile("s_waitcnt lgkmcnt(" #n ")" ::: "memory")
; #define PG8_BAR __builtin_amdgcn_s_barrier()
; #define PG8_SCHED __builtin_amdgcn_sched_barrier(0)
; template <class Epi, class Sched, bool ALIGN_EPI = false, bool SP2 = false>
; __device__ __forceinline__ void gemm_phase(PG8_LAS unsigned char* lds, const Gemm g, const Sched& S, const Epi& E) {
;     ...
;             const bool last = (t == nt - 2);
;             const char* a1 = cA + (size_t)(t + 1) * kstep;
;             const char* a2 = last ? nA : cA + (size_t)(t + 2) * kstep; const char* b2 = last ? nB : cB + (size_t)(t + 2) * kstep;
;             const char* a3 = a2 + kstep; const char* b3 = b2 + kstep;
;             if (last && has_next) S.a_ready(nxt);
;             if constexpr (SP2) {
;             PG8_LDB(B0, 0, 0); PG8_LDB(B1, 0, 1); PG8_SCHED; PG8_LDA(At, 0, 0); PG8_STAGE(PG8_SA(1, 1), a1 + hstep, voffA);
;             PG8_WAIT_V(8); PG8_WAIT_L(0); PG8_BAR; PG8_MMA(0, 0, At, B0); PG8_MMA(0, 1, At, B1); PG8_BAR; PG8_SCHED;
;     ...
;             PG8_WAIT_V(8); PG8_WAIT_L(0); PG8_BAR; PG8_MMA(1, 0, At, B0); PG8_MMA(1, 1, At, B1); PG8_BAR; PG8_SCHED;
	s_setprio 1
	v_mfma_f32_16x16x32_bf16 v[64:67], v[108:111], v[164:167], 0
	v_mfma_f32_16x16x32_bf16 v[60:63], v[124:127], v[164:167], 0
	v_mfma_f32_16x16x32_bf16 v[48:51], v[108:111], v[172:175], 0
	v_mfma_f32_16x16x32_bf16 v[44:47], v[124:127], v[172:175], 0
	v_mfma_f32_16x16x32_bf16 v[32:35], v[108:111], v[180:183], 0
	v_mfma_f32_16x16x32_bf16 v[28:31], v[124:127], v[180:183], 0
	v_mfma_f32_16x16x32_bf16 v[16:19], v[108:111], v[188:191], 0
	v_mfma_f32_16x16x32_bf16 v[12:15], v[124:127], v[188:191], 0
	v_mfma_f32_16x16x32_bf16 v[64:67], v[112:115], v[168:171], v[64:67]
	v_mfma_f32_16x16x32_bf16 v[60:63], v[128:131], v[168:171], v[60:63]
	v_mfma_f32_16x16x32_bf16 v[48:51], v[112:115], v[176:179], v[48:51]
	v_mfma_f32_16x16x32_bf16 v[44:47], v[128:131], v[176:179], v[44:47]
	v_mfma_f32_16x16x32_bf16 v[32:35], v[112:115], v[184:187], v[32:35]
	v_mfma_f32_16x16x32_bf16 v[28:31], v[128:131], v[184:187], v[28:31]
	v_mfma_f32_16x16x32_bf16 v[16:19], v[112:115], v[192:195], v[16:19]
	v_mfma_f32_16x16x32_bf16 v[12:15], v[128:131], v[192:195], v[12:15]
	s_setprio 0
	s_setprio 1
	v_mfma_f32_16x16x32_bf16 v[56:59], v[132:135], v[164:167], 0
	v_mfma_f32_16x16x32_bf16 v[52:55], v[148:151], v[164:167], 0
	v_mfma_f32_16x16x32_bf16 v[40:43], v[132:135], v[172:175], 0
	v_mfma_f32_16x16x32_bf16 v[36:39], v[148:151], v[172:175], 0
	v_mfma_f32_16x16x32_bf16 v[24:27], v[132:135], v[180:183], 0
	v_mfma_f32_16x16x32_bf16 v[20:23], v[148:151], v[180:183], 0
	v_mfma_f32_16x16x32_bf16 v[8:11], v[132:135], v[188:191], 0
	v_mfma_f32_16x16x32_bf16 v[4:7], v[148:151], v[188:191], 0
	v_mfma_f32_16x16x32_bf16 v[56:59], v[140:143], v[168:171], v[56:59]
	v_mfma_f32_16x16x32_bf16 v[52:55], v[156:159], v[168:171], v[52:55]
	v_mfma_f32_16x16x32_bf16 v[40:43], v[140:143], v[176:179], v[40:43]
	v_mfma_f32_16x16x32_bf16 v[36:39], v[156:159], v[176:179], v[36:39]
	v_mfma_f32_16x16x32_bf16 v[24:27], v[140:143], v[184:187], v[24:27]
	v_mfma_f32_16x16x32_bf16 v[20:23], v[156:159], v[184:187], v[20:23]
	v_mfma_f32_16x16x32_bf16 v[8:11], v[140:143], v[192:195], v[8:11]
	v_mfma_f32_16x16x32_bf16 v[4:7], v[156:159], v[192:195], v[4:7]
	s_setprio 0
	s_barrier
	s_branch .Lkmid_1
.LBB0_329:
	s_add_u32 s30, s28, 0xfffc0080
	s_addc_u32 s31, s29, -1
	s_cmp_eq_u32 s45, 12
	s_cselect_b32 s35, s3, s31
	s_cselect_b32 s34, s17, s30
	s_cselect_b32 s31, s19, s44
	s_cselect_b32 s30, s25, s27
	s_add_i32 m0, s49, 0xffffff80
	ds_read_b128 v[108:111], v251
	ds_read_b128 v[112:115], v251 offset:1024
	ds_read_b128 v[124:127], v251 offset:2048
	ds_read_b128 v[128:131], v251 offset:3072
	ds_read_b128 v[132:135], v251 offset:16384
	ds_read_b128 v[140:143], v251 offset:17408
	ds_read_b128 v[148:151], v251 offset:18432
	ds_read_b128 v[156:159], v251 offset:19456
	global_load_lds_dwordx4 v[216:217], off offset:128
	s_add_i32 m0, s50, 0xffffff80
	v_lshl_add_u64 v[212:213], s[28:29], 0, v[208:209]
	global_load_lds_dwordx4 v[218:219], off offset:128
	s_add_i32 m0, s42, 0xc000
	ds_read_b128 v[164:167], v253
	ds_read_b128 v[168:171], v253 offset:1024
	ds_read_b128 v[172:175], v253 offset:2048
	ds_read_b128 v[176:179], v253 offset:3072
	ds_read_b128 v[180:183], v253 offset:4096
	ds_read_b128 v[184:187], v253 offset:5120
	ds_read_b128 v[188:191], v253 offset:6144
	ds_read_b128 v[192:195], v253 offset:7168
	global_load_lds_dwordx4 v[212:213], off
	s_add_i32 m0, s42, 0xe000
	v_lshl_add_u64 v[212:213], s[28:29], 0, v[210:211]
	global_load_lds_dwordx4 v[212:213], off
	s_waitcnt vmcnt(8) lgkmcnt(0)
	s_barrier
	s_setprio 1
	v_mfma_f32_16x16x32_bf16 v[160:163], v[108:111], v[164:167], v[160:163]
	v_mfma_f32_16x16x32_bf16 v[152:155], v[124:127], v[164:167], v[152:155]
	v_mfma_f32_16x16x32_bf16 v[120:123], v[108:111], v[172:175], v[120:123]
	v_mfma_f32_16x16x32_bf16 v[116:119], v[124:127], v[172:175], v[116:119]
	v_mfma_f32_16x16x32_bf16 v[96:99], v[108:111], v[180:183], v[96:99]
	v_mfma_f32_16x16x32_bf16 v[92:95], v[124:127], v[180:183], v[92:95]
	v_mfma_f32_16x16x32_bf16 v[80:83], v[108:111], v[188:191], v[80:83]
	v_mfma_f32_16x16x32_bf16 v[76:79], v[124:127], v[188:191], v[76:79]
	v_mfma_f32_16x16x32_bf16 v[160:163], v[112:115], v[168:171], v[160:163]
	v_mfma_f32_16x16x32_bf16 v[152:155], v[128:131], v[168:171], v[152:155]
	v_mfma_f32_16x16x32_bf16 v[120:123], v[112:115], v[176:179], v[120:123]
	v_mfma_f32_16x16x32_bf16 v[116:119], v[128:131], v[176:179], v[116:119]
	v_mfma_f32_16x16x32_bf16 v[96:99], v[112:115], v[184:187], v[96:99]
	v_mfma_f32_16x16x32_bf16 v[92:95], v[128:131], v[184:187], v[92:95]
	v_mfma_f32_16x16x32_bf16 v[80:83], v[112:115], v[192:195], v[80:83]
	v_mfma_f32_16x16x32_bf16 v[76:79], v[128:131], v[192:195], v[76:79]
	s_setprio 0
	s_setprio 1
	v_mfma_f32_16x16x32_bf16 v[144:147], v[132:135], v[164:167], v[144:147]
	v_mfma_f32_16x16x32_bf16 v[136:139], v[148:151], v[164:167], v[136:139]
	v_mfma_f32_16x16x32_bf16 v[104:107], v[132:135], v[172:175], v[104:107]
	v_mfma_f32_16x16x32_bf16 v[100:103], v[148:151], v[172:175], v[100:103]
	v_mfma_f32_16x16x32_bf16 v[88:91], v[132:135], v[180:183], v[88:91]
	v_mfma_f32_16x16x32_bf16 v[84:87], v[148:151], v[180:183], v[84:87]
	v_mfma_f32_16x16x32_bf16 v[72:75], v[132:135], v[188:191], v[72:75]
	v_mfma_f32_16x16x32_bf16 v[68:71], v[148:151], v[188:191], v[68:71]
	v_mfma_f32_16x16x32_bf16 v[144:147], v[140:143], v[168:171], v[144:147]
	v_mfma_f32_16x16x32_bf16 v[136:139], v[156:159], v[168:171], v[136:139]
	v_mfma_f32_16x16x32_bf16 v[104:107], v[140:143], v[176:179], v[104:107]
	v_mfma_f32_16x16x32_bf16 v[100:103], v[156:159], v[176:179], v[100:103]
	v_mfma_f32_16x16x32_bf16 v[88:91], v[140:143], v[184:187], v[88:91]
	v_mfma_f32_16x16x32_bf16 v[84:87], v[156:159], v[184:187], v[84:87]
	v_mfma_f32_16x16x32_bf16 v[72:75], v[140:143], v[192:195], v[72:75]
	v_mfma_f32_16x16x32_bf16 v[68:71], v[156:159], v[192:195], v[68:71]
	s_setprio 0
	s_barrier
; #define PG8_STAGE(bufoff, gbase, voff) do { _Pragma("unroll") for (int _i = 0; _i < 2; ++_i) \
;         __builtin_amdgcn_global_load_lds((const unsigned*)((const char*)(gbase) + (voff)[_i]), (PG8_LAS unsigned*)(lds + (bufoff) + ldsw + _i * 8192), 16, 0, 0); } while (0)
; #define PG8_LDA(dst, b, h) do { _Pragma("unroll") for (int m = 0; m < 4; ++m) _Pragma("unroll") for (int k = 0; k < 2; ++k) dst[m][k] = *(const PG8_LAS bf16x8*)(lds + PG8_SA(b, h) + aoff + m * 2048 + k * 1024); } while (0)
; #define PG8_MMA(ai, bj, At, Bt) do { __builtin_amdgcn_s_setprio(1); _Pragma("unroll") for (int m = 0; m < 4; ++m) _Pragma("unroll") for (int n = 0; n < 2; ++n) _Pragma("unroll") for (int k = 0; k < 2; ++k) \
;         acc[ai][bj][m][n] = __builtin_amdgcn_mfma_f32_16x16x32_bf16(Bt[n][k], At[m][k], acc[ai][bj][m][n], 0, 0, 0); __builtin_amdgcn_s_setprio(0); } while (0)
; #define PG8_WAIT_V(n) asm volatile("s_waitcnt vmcnt(" #n ")" ::: "memory")
; #define PG8_WAIT_L(n) asm volatile("s_waitcnt lgkmcnt(" #n ")" ::: "memory")
; #define PG8_BAR __builtin_amdgcn_s_barrier()
; #define PG8_SCHED __builtin_amdgcn_sched_barrier(0)
; template <class Epi, class Sched, bool ALIGN_EPI = false, bool SP2 = false>
; __device__ __forceinline__ void gemm_phase(PG8_LAS unsigned char* lds, const Gemm g, const Sched& S, const Epi& E) {
;     ...
;             PG8_LDA(At, 0, 1); PG8_STAGE(PG8_SB(0, 0), b2, voffB); PG8_STAGE(PG8_SB(0, 1), b2 + hstep, voffB); PG8_STAGE(PG8_SA(0, 0), a2, voffA);
;             PG8_WAIT_V(8); PG8_WAIT_L(0); PG8_BAR; PG8_MMA(1, 0, At, B0); PG8_MMA(1, 1, At, B1); PG8_BAR; PG8_SCHED;
	v_lshl_add_u64 v[212:213], s[30:31], 0, v[202:203]
	s_add_i32 m0, s41, 0x10000
	ds_read_b128 v[164:167], v253 offset:16384
	ds_read_b128 v[168:171], v253 offset:17408
	ds_read_b128 v[172:175], v253 offset:18432
	ds_read_b128 v[176:179], v253 offset:19456
	ds_read_b128 v[180:183], v253 offset:20480
	ds_read_b128 v[184:187], v253 offset:21504
	ds_read_b128 v[188:191], v253 offset:22528
	ds_read_b128 v[192:195], v253 offset:23552
	global_load_lds_dwordx4 v[212:213], off
	s_add_i32 m0, s41, 0x12000
	s_add_u32 s52, s30, 0x40000
	v_lshl_add_u64 v[214:215], s[30:31], 0, v[206:207]
	s_addc_u32 s53, s31, 0
	global_load_lds_dwordx4 v[214:215], off
	v_lshl_add_u64 v[244:245], s[52:53], 0, v[202:203]
	s_add_i32 m0, s41, 0x14000
	v_lshl_add_u64 v[218:219], s[34:35], 0, v[204:205]
	global_load_lds_dwordx4 v[244:245], off
	s_add_i32 m0, s41, 0x16000
	v_lshl_add_u64 v[246:247], s[52:53], 0, v[206:207]
	global_load_lds_dwordx4 v[246:247], off
	v_lshl_add_u64 v[216:217], s[34:35], 0, v[0:1]
	s_waitcnt vmcnt(6) lgkmcnt(0)
	s_barrier
	s_setprio 1
	v_mfma_f32_16x16x32_bf16 v[64:67], v[108:111], v[164:167], v[64:67]
	v_mfma_f32_16x16x32_bf16 v[60:63], v[124:127], v[164:167], v[60:63]
	v_mfma_f32_16x16x32_bf16 v[48:51], v[108:111], v[172:175], v[48:51]
	v_mfma_f32_16x16x32_bf16 v[44:47], v[124:127], v[172:175], v[44:47]
	v_mfma_f32_16x16x32_bf16 v[32:35], v[108:111], v[180:183], v[32:35]
	v_mfma_f32_16x16x32_bf16 v[28:31], v[124:127], v[180:183], v[28:31]
	v_mfma_f32_16x16x32_bf16 v[16:19], v[108:111], v[188:191], v[16:19]
	v_mfma_f32_16x16x32_bf16 v[12:15], v[124:127], v[188:191], v[12:15]
	v_mfma_f32_16x16x32_bf16 v[64:67], v[112:115], v[168:171], v[64:67]
	v_mfma_f32_16x16x32_bf16 v[60:63], v[128:131], v[168:171], v[60:63]
	v_mfma_f32_16x16x32_bf16 v[48:51], v[112:115], v[176:179], v[48:51]
	v_mfma_f32_16x16x32_bf16 v[44:47], v[128:131], v[176:179], v[44:47]
	v_mfma_f32_16x16x32_bf16 v[32:35], v[112:115], v[184:187], v[32:35]
	v_mfma_f32_16x16x32_bf16 v[28:31], v[128:131], v[184:187], v[28:31]
	v_mfma_f32_16x16x32_bf16 v[16:19], v[112:115], v[192:195], v[16:19]
	v_mfma_f32_16x16x32_bf16 v[12:15], v[128:131], v[192:195], v[12:15]
	s_setprio 0
	s_setprio 1
	v_mfma_f32_16x16x32_bf16 v[56:59], v[132:135], v[164:167], v[56:59]
	v_mfma_f32_16x16x32_bf16 v[52:55], v[148:151], v[164:167], v[52:55]
	v_mfma_f32_16x16x32_bf16 v[40:43], v[132:135], v[172:175], v[40:43]
	v_mfma_f32_16x16x32_bf16 v[36:39], v[148:151], v[172:175], v[36:39]
	v_mfma_f32_16x16x32_bf16 v[24:27], v[132:135], v[180:183], v[24:27]
	v_mfma_f32_16x16x32_bf16 v[20:23], v[148:151], v[180:183], v[20:23]
	v_mfma_f32_16x16x32_bf16 v[8:11], v[132:135], v[188:191], v[8:11]
	v_mfma_f32_16x16x32_bf16 v[4:7], v[148:151], v[188:191], v[4:7]
	v_mfma_f32_16x16x32_bf16 v[56:59], v[140:143], v[168:171], v[56:59]
	v_mfma_f32_16x16x32_bf16 v[52:55], v[156:159], v[168:171], v[52:55]
	v_mfma_f32_16x16x32_bf16 v[40:43], v[140:143], v[176:179], v[40:43]
	v_mfma_f32_16x16x32_bf16 v[36:39], v[156:159], v[176:179], v[36:39]
	v_mfma_f32_16x16x32_bf16 v[24:27], v[140:143], v[184:187], v[24:27]
	v_mfma_f32_16x16x32_bf16 v[20:23], v[156:159], v[184:187], v[20:23]
	v_mfma_f32_16x16x32_bf16 v[8:11], v[140:143], v[192:195], v[8:11]
	v_mfma_f32_16x16x32_bf16 v[4:7], v[156:159], v[192:195], v[4:7]
	s_setprio 0
	s_barrier
; #define PG8_STAGE(bufoff, gbase, voff) do { _Pragma("unroll") for (int _i = 0; _i < 2; ++_i) \
;         __builtin_amdgcn_global_load_lds((const unsigned*)((const char*)(gbase) + (voff)[_i]), (PG8_LAS unsigned*)(lds + (bufoff) + ldsw + _i * 8192), 16, 0, 0); } while (0)
; #define PG8_LDA(dst, b, h) do { _Pragma("unroll") for (int m = 0; m < 4; ++m) _Pragma("unroll") for (int k = 0; k < 2; ++k) dst[m][k] = *(const PG8_LAS bf16x8*)(lds + PG8_SA(b, h) + aoff + m * 2048 + k * 1024); } while (0)
; #define PG8_LDB(dst, b, h) do { _Pragma("unroll") for (int n = 0; n < 2; ++n) _Pragma("unroll") for (int k = 0; k < 2; ++k) dst[n][k] = *(const PG8_LAS bf16x8*)(lds + PG8_SB(b, h) + boff + n * 2048 + k * 1024); } while (0)
; #define PG8_MMA(ai, bj, At, Bt) do { __builtin_amdgcn_s_setprio(1); _Pragma("unroll") for (int m = 0; m < 4; ++m) _Pragma("unroll") for (int n = 0; n < 2; ++n) _Pragma("unroll") for (int k = 0; k < 2; ++k) \
;         acc[ai][bj][m][n] = __builtin_amdgcn_mfma_f32_16x16x32_bf16(Bt[n][k], At[m][k], acc[ai][bj][m][n], 0, 0, 0); __builtin_amdgcn_s_setprio(0); } while (0)
; #define PG8_WAIT_V(n) asm volatile("s_waitcnt vmcnt(" #n ")" ::: "memory")
; #define PG8_WAIT_L(n) asm volatile("s_waitcnt lgkmcnt(" #n ")" ::: "memory")
; #define PG8_BAR __builtin_amdgcn_s_barrier()
; #define PG8_SCHED __builtin_amdgcn_sched_barrier(0)
; template <class Epi, class Sched, bool ALIGN_EPI = false, bool SP2 = false>
; __device__ __forceinline__ void gemm_phase(PG8_LAS unsigned char* lds, const Gemm g, const Sched& S, const Epi& E) {
;     ...
;             PG8_LDB(B0, 1, 0); PG8_LDB(B1, 1, 1); PG8_SCHED; PG8_LDA(At, 1, 0); PG8_STAGE(PG8_SA(0, 1), a2 + hstep, voffA);
;             PG8_WAIT_V(8); PG8_WAIT_L(0); PG8_BAR; PG8_MMA(0, 0, At, B0); PG8_MMA(0, 1, At, B1); PG8_BAR; PG8_SCHED;
;             PG8_LDA(At, 1, 1); PG8_STAGE(PG8_SB(1, 0), b3, voffB); PG8_STAGE(PG8_SB(1, 1), b3 + hstep, voffB); PG8_STAGE(PG8_SA(1, 0), a3, voffA);
;             PG8_WAIT_V(8); PG8_WAIT_L(0); PG8_BAR; PG8_MMA(1, 0, At, B0); PG8_MMA(1, 1, At, B1); PG8_BAR; PG8_SCHED;
.Lkmid_1:
	ds_read_b128 v[108:111], v251 offset:32768
	ds_read_b128 v[112:115], v251 offset:33792
	ds_read_b128 v[124:127], v251 offset:34816
	ds_read_b128 v[128:131], v251 offset:35840
	ds_read_b128 v[132:135], v251 offset:49152
	ds_read_b128 v[140:143], v251 offset:50176
	ds_read_b128 v[148:151], v251 offset:51200
	ds_read_b128 v[156:159], v251 offset:52224
	s_mov_b32 m0, s42
	s_add_u32 s34, s34, 0x40000
	s_addc_u32 s35, s35, 0
	global_load_lds_dwordx4 v[216:217], off
	s_mov_b32 m0, s43
	v_lshl_add_u64 v[220:221], s[34:35], 0, v[0:1]
	global_load_lds_dwordx4 v[218:219], off
	s_mov_b32 m0, s46
	ds_read_b128 v[164:167], v253 offset:32768
	ds_read_b128 v[168:171], v253 offset:33792
	ds_read_b128 v[172:175], v253 offset:34816
	ds_read_b128 v[176:179], v253 offset:35840
	ds_read_b128 v[180:183], v253 offset:36864
	ds_read_b128 v[184:187], v253 offset:37888
	ds_read_b128 v[188:191], v253 offset:38912
	ds_read_b128 v[192:195], v253 offset:39936
	global_load_lds_dwordx4 v[220:221], off
	s_mov_b32 m0, s47
	v_lshl_add_u64 v[220:221], s[34:35], 0, v[204:205]
	global_load_lds_dwordx4 v[220:221], off
	s_waitcnt vmcnt(8) lgkmcnt(0)
	s_barrier
	s_setprio 1
	v_mfma_f32_16x16x32_bf16 v[160:163], v[108:111], v[164:167], v[160:163]
	v_mfma_f32_16x16x32_bf16 v[152:155], v[124:127], v[164:167], v[152:155]
	v_mfma_f32_16x16x32_bf16 v[120:123], v[108:111], v[172:175], v[120:123]
	v_mfma_f32_16x16x32_bf16 v[116:119], v[124:127], v[172:175], v[116:119]
	v_mfma_f32_16x16x32_bf16 v[96:99], v[108:111], v[180:183], v[96:99]
	v_mfma_f32_16x16x32_bf16 v[92:95], v[124:127], v[180:183], v[92:95]
	v_mfma_f32_16x16x32_bf16 v[80:83], v[108:111], v[188:191], v[80:83]
	v_mfma_f32_16x16x32_bf16 v[76:79], v[124:127], v[188:191], v[76:79]
	v_mfma_f32_16x16x32_bf16 v[160:163], v[112:115], v[168:171], v[160:163]
	v_mfma_f32_16x16x32_bf16 v[152:155], v[128:131], v[168:171], v[152:155]
	v_mfma_f32_16x16x32_bf16 v[120:123], v[112:115], v[176:179], v[120:123]
	v_mfma_f32_16x16x32_bf16 v[116:119], v[128:131], v[176:179], v[116:119]
	v_mfma_f32_16x16x32_bf16 v[96:99], v[112:115], v[184:187], v[96:99]
	v_mfma_f32_16x16x32_bf16 v[92:95], v[128:131], v[184:187], v[92:95]
	v_mfma_f32_16x16x32_bf16 v[80:83], v[112:115], v[192:195], v[80:83]
	v_mfma_f32_16x16x32_bf16 v[76:79], v[128:131], v[192:195], v[76:79]
	s_setprio 0
	s_setprio 1
	v_mfma_f32_16x16x32_bf16 v[144:147], v[132:135], v[164:167], v[144:147]
	v_mfma_f32_16x16x32_bf16 v[136:139], v[148:151], v[164:167], v[136:139]
	v_mfma_f32_16x16x32_bf16 v[104:107], v[132:135], v[172:175], v[104:107]
	v_mfma_f32_16x16x32_bf16 v[100:103], v[148:151], v[172:175], v[100:103]
	v_mfma_f32_16x16x32_bf16 v[88:91], v[132:135], v[180:183], v[88:91]
	v_mfma_f32_16x16x32_bf16 v[84:87], v[148:151], v[180:183], v[84:87]
	v_mfma_f32_16x16x32_bf16 v[72:75], v[132:135], v[188:191], v[72:75]
	v_mfma_f32_16x16x32_bf16 v[68:71], v[148:151], v[188:191], v[68:71]
	v_mfma_f32_16x16x32_bf16 v[144:147], v[140:143], v[168:171], v[144:147]
	v_mfma_f32_16x16x32_bf16 v[136:139], v[156:159], v[168:171], v[136:139]
	v_mfma_f32_16x16x32_bf16 v[104:107], v[140:143], v[176:179], v[104:107]
	v_mfma_f32_16x16x32_bf16 v[100:103], v[156:159], v[176:179], v[100:103]
	v_mfma_f32_16x16x32_bf16 v[88:91], v[140:143], v[184:187], v[88:91]
	v_mfma_f32_16x16x32_bf16 v[84:87], v[156:159], v[184:187], v[84:87]
	v_mfma_f32_16x16x32_bf16 v[72:75], v[140:143], v[192:195], v[72:75]
	v_mfma_f32_16x16x32_bf16 v[68:71], v[156:159], v[192:195], v[68:71]
	s_setprio 0
	s_barrier
	s_add_i32 m0, s41, 0x17f80
	ds_read_b128 v[164:167], v253 offset:49152
	ds_read_b128 v[168:171], v253 offset:50176
	ds_read_b128 v[172:175], v253 offset:51200
	ds_read_b128 v[176:179], v253 offset:52224
	ds_read_b128 v[180:183], v253 offset:53248
	ds_read_b128 v[184:187], v253 offset:54272
	ds_read_b128 v[188:191], v253 offset:55296
	ds_read_b128 v[192:195], v253 offset:56320
	global_load_lds_dwordx4 v[212:213], off offset:128
	s_add_i32 m0, s41, 0x19f80
	s_add_u32 s28, s28, 0x100
	s_addc_u32 s29, s29, 0
	global_load_lds_dwordx4 v[214:215], off offset:128
	s_add_i32 m0, s41, 0x1bf80
	s_add_u32 s27, s27, 0x100
	s_addc_u32 s44, s44, 0
	global_load_lds_dwordx4 v[244:245], off offset:128
	s_add_i32 m0, s41, 0x1df80
	s_cmp_eq_u32 s45, 12
	global_load_lds_dwordx4 v[246:247], off offset:128
	s_cbranch_scc0 .Lks4_1
	s_add_i32 m0, s49, 0xffffff80
	s_nop 0
	global_load_lds_dwordx4 v[216:217], off offset:128
	s_add_i32 m0, s50, 0xffffff80
	s_nop 0
	global_load_lds_dwordx4 v[218:219], off offset:128
.Lks4_1:
	s_waitcnt vmcnt(6) lgkmcnt(0)
	s_barrier
	s_setprio 1
	v_mfma_f32_16x16x32_bf16 v[64:67], v[108:111], v[164:167], v[64:67]
	v_mfma_f32_16x16x32_bf16 v[60:63], v[124:127], v[164:167], v[60:63]
	v_mfma_f32_16x16x32_bf16 v[48:51], v[108:111], v[172:175], v[48:51]
	v_mfma_f32_16x16x32_bf16 v[44:47], v[124:127], v[172:175], v[44:47]
	v_mfma_f32_16x16x32_bf16 v[32:35], v[108:111], v[180:183], v[32:35]
	v_mfma_f32_16x16x32_bf16 v[28:31], v[124:127], v[180:183], v[28:31]
	v_mfma_f32_16x16x32_bf16 v[16:19], v[108:111], v[188:191], v[16:19]
	v_mfma_f32_16x16x32_bf16 v[12:15], v[124:127], v[188:191], v[12:15]
	v_mfma_f32_16x16x32_bf16 v[64:67], v[112:115], v[168:171], v[64:67]
	v_mfma_f32_16x16x32_bf16 v[60:63], v[128:131], v[168:171], v[60:63]
	v_mfma_f32_16x16x32_bf16 v[48:51], v[112:115], v[176:179], v[48:51]
	v_mfma_f32_16x16x32_bf16 v[44:47], v[128:131], v[176:179], v[44:47]
	v_mfma_f32_16x16x32_bf16 v[32:35], v[112:115], v[184:187], v[32:35]
	v_mfma_f32_16x16x32_bf16 v[28:31], v[128:131], v[184:187], v[28:31]
	v_mfma_f32_16x16x32_bf16 v[16:19], v[112:115], v[192:195], v[16:19]
	v_mfma_f32_16x16x32_bf16 v[12:15], v[128:131], v[192:195], v[12:15]
	s_setprio 0
	s_setprio 1
	v_mfma_f32_16x16x32_bf16 v[56:59], v[132:135], v[164:167], v[56:59]
	v_mfma_f32_16x16x32_bf16 v[52:55], v[148:151], v[164:167], v[52:55]
	v_mfma_f32_16x16x32_bf16 v[40:43], v[132:135], v[172:175], v[40:43]
	v_mfma_f32_16x16x32_bf16 v[36:39], v[148:151], v[172:175], v[36:39]
	v_mfma_f32_16x16x32_bf16 v[24:27], v[132:135], v[180:183], v[24:27]
	v_mfma_f32_16x16x32_bf16 v[20:23], v[148:151], v[180:183], v[20:23]
	v_mfma_f32_16x16x32_bf16 v[8:11], v[132:135], v[188:191], v[8:11]
	v_mfma_f32_16x16x32_bf16 v[4:7], v[148:151], v[188:191], v[4:7]
	v_mfma_f32_16x16x32_bf16 v[56:59], v[140:143], v[168:171], v[56:59]
	v_mfma_f32_16x16x32_bf16 v[52:55], v[156:159], v[168:171], v[52:55]
	v_mfma_f32_16x16x32_bf16 v[40:43], v[140:143], v[176:179], v[40:43]
	v_mfma_f32_16x16x32_bf16 v[36:39], v[156:159], v[176:179], v[36:39]
	v_mfma_f32_16x16x32_bf16 v[24:27], v[140:143], v[184:187], v[24:27]
	v_mfma_f32_16x16x32_bf16 v[20:23], v[156:159], v[184:187], v[20:23]
	v_mfma_f32_16x16x32_bf16 v[8:11], v[140:143], v[192:195], v[8:11]
	v_mfma_f32_16x16x32_bf16 v[4:7], v[156:159], v[192:195], v[4:7]
	s_setprio 0
	s_barrier
	s_add_i32 s45, s45, 2
	s_cmp_gt_u32 s45, 13
	s_cbranch_scc0 .LBB0_329
	s_and_b64 vcc, exec, s[14:15]
	s_cbranch_vccz .LBB0_332
	s_barrier

; #define PG8_STAGE(bufoff, gbase, voff) do { _Pragma("unroll") for (int _i = 0; _i < 2; ++_i) \
;         __builtin_amdgcn_global_load_lds((const unsigned*)((const char*)(gbase) + (voff)[_i]), (PG8_LAS unsigned*)(lds + (bufoff) + ldsw + _i * 8192), 16, 0, 0); } while (0)
; #define PG8_LDA(dst, b, h) do { _Pragma("unroll") for (int m = 0; m < 4; ++m) _Pragma("unroll") for (int k = 0; k < 2; ++k) dst[m][k] = *(const PG8_LAS bf16x8*)(lds + PG8_SA(b, h) + aoff + m * 2048 + k * 1024); } while (0)
; #define PG8_LDB(dst, b, h) do { _Pragma("unroll") for (int n = 0; n < 2; ++n) _Pragma("unroll") for (int k = 0; k < 2; ++k) dst[n][k] = *(const PG8_LAS bf16x8*)(lds + PG8_SB(b, h) + boff + n * 2048 + k * 1024); } while (0)
; #define PG8_WAIT_V(n) asm volatile("s_waitcnt vmcnt(" #n ")" ::: "memory")
; #define PG8_WAIT_L(n) asm volatile("s_waitcnt lgkmcnt(" #n ")" ::: "memory")
; #define PG8_BAR __builtin_amdgcn_s_barrier()
; #define PG8_SCHED __builtin_amdgcn_sched_barrier(0)
; template <class Epi, class Sched, bool ALIGN_EPI = false, bool SP2 = false>
; __device__ __forceinline__ void gemm_phase(PG8_LAS unsigned char* lds, const Gemm g, const Sched& S, const Epi& E) {
;     ...
;         const char* nA = has_next ? (const char*)g.A + (size_t)nxt.pm * tstep : cA; const char* nB = has_next ? (const char*)g.Bt + (size_t)nxt.pn * tstep : cB;
;         for (int t = 0; t < nt; t += 2) {
;             const bool last = (t == nt - 2);
;             const char* a1 = cA + (size_t)(t + 1) * kstep;
;             const char* a2 = last ? nA : cA + (size_t)(t + 2) * kstep; const char* b2 = last ? nB : cB + (size_t)(t + 2) * kstep;
;             const char* a3 = a2 + kstep; const char* b3 = b2 + kstep;
;             if (last && has_next) S.a_ready(nxt);
;             if constexpr (SP2) {
;             PG8_LDB(B0, 0, 0); PG8_LDB(B1, 0, 1); PG8_SCHED; PG8_LDA(At, 0, 0); PG8_STAGE(PG8_SA(1, 1), a1 + hstep, voffA);
;             PG8_WAIT_V(8); PG8_WAIT_L(0); PG8_BAR; PG8_MMA(0, 0, At, B0); PG8_MMA(0, 1, At, B1); PG8_BAR; PG8_SCHED;
;             PG8_LDA(At, 0, 1); PG8_STAGE(PG8_SB(0, 0), b2, voffB); PG8_STAGE(PG8_SB(0, 1), b2 + hstep, voffB); PG8_STAGE(PG8_SA(0, 0), a2, voffA);
;             PG8_WAIT_V(8); PG8_WAIT_L(0); PG8_BAR; PG8_MMA(1, 0, At, B0); PG8_MMA(1, 1, At, B1); PG8_BAR; PG8_SCHED;
.LBB0_404:
	s_ashr_i32 s17, s16, 31
	s_lshl_b64 s[20:21], s[16:17], 19
	s_add_u32 s20, s29, s20
	s_addc_u32 s21, s30, s21
	s_and_b64 s[22:23], s[4:5], exec
	s_cselect_b32 s7, s21, s9
	s_cselect_b32 s17, s20, s8
	s_ashr_i32 s19, s18, 31
	s_lshl_b64 s[22:23], s[18:19], 19
	s_add_u32 s22, s31, s22
	s_addc_u32 s23, s34, s23
	s_and_b64 s[26:27], s[4:5], exec
	s_cselect_b32 s19, s23, s25
	s_cselect_b32 s43, s22, s24
	s_add_u32 s8, s8, 0x40080
	s_addc_u32 s9, s9, 0
	s_add_u32 s44, s24, 0x100
	s_addc_u32 s45, s25, 0
	s_mov_b32 s46, -2
	s_add_u32 s24, s8, 0xfffc0080
	s_addc_u32 s25, s9, -1
	s_cmp_eq_u32 s46, 12
	s_cselect_b32 s27, s7, s25
	s_cselect_b32 s26, s17, s24
	s_cselect_b32 s25, s19, s45
	s_cselect_b32 s24, s43, s44
	s_add_i32 s50, 0, 0x14000
	ds_read_b128 v[144:147], v164
	ds_read_b128 v[148:151], v164 offset:1024
	ds_read_b128 v[152:155], v164 offset:2048
	ds_read_b128 v[156:159], v164 offset:3072
	ds_read_b128 v[160:163], v164 offset:16384
	ds_read_b128 v[168:171], v164 offset:17408
	ds_read_b128 v[172:175], v164 offset:18432
	ds_read_b128 v[176:179], v164 offset:19456
	v_lshl_add_u64 v[198:199], s[8:9], 0, v[140:141]
	s_add_i32 m0, s37, 0xc000
	ds_read_b128 v[180:183], v166
	ds_read_b128 v[184:187], v166 offset:1024
	ds_read_b128 v[188:191], v166 offset:2048
	ds_read_b128 v[192:195], v166 offset:3072
	ds_read_b128 v[202:205], v166 offset:4096
	ds_read_b128 v[206:209], v166 offset:5120
	ds_read_b128 v[210:213], v166 offset:6144
	ds_read_b128 v[214:217], v166 offset:7168
	global_load_lds_dwordx4 v[198:199], off
	s_add_i32 m0, s37, 0xe000
	v_lshl_add_u64 v[198:199], s[8:9], 0, v[142:143]
	global_load_lds_dwordx4 v[198:199], off
	s_waitcnt vmcnt(8) lgkmcnt(0)
	s_barrier
	s_setprio 1
	v_mfma_f32_16x16x32_bf16 v[128:131], v[144:147], v[180:183], 0
	v_mfma_f32_16x16x32_bf16 v[120:123], v[152:155], v[180:183], 0
	v_mfma_f32_16x16x32_bf16 v[112:115], v[144:147], v[188:191], 0
	v_mfma_f32_16x16x32_bf16 v[104:107], v[152:155], v[188:191], 0
	v_mfma_f32_16x16x32_bf16 v[96:99], v[144:147], v[202:205], 0
	v_mfma_f32_16x16x32_bf16 v[88:91], v[152:155], v[202:205], 0
	v_mfma_f32_16x16x32_bf16 v[80:83], v[144:147], v[210:213], 0
	v_mfma_f32_16x16x32_bf16 v[72:75], v[152:155], v[210:213], 0
	v_mfma_f32_16x16x32_bf16 v[128:131], v[148:151], v[184:187], v[128:131]
	v_mfma_f32_16x16x32_bf16 v[120:123], v[156:159], v[184:187], v[120:123]
	v_mfma_f32_16x16x32_bf16 v[112:115], v[148:151], v[192:195], v[112:115]
	v_mfma_f32_16x16x32_bf16 v[104:107], v[156:159], v[192:195], v[104:107]
	v_mfma_f32_16x16x32_bf16 v[96:99], v[148:151], v[206:209], v[96:99]
	v_mfma_f32_16x16x32_bf16 v[88:91], v[156:159], v[206:209], v[88:91]
	v_mfma_f32_16x16x32_bf16 v[80:83], v[148:151], v[214:217], v[80:83]
	v_mfma_f32_16x16x32_bf16 v[72:75], v[156:159], v[214:217], v[72:75]
	s_setprio 0
	s_setprio 1
	v_mfma_f32_16x16x32_bf16 v[124:127], v[160:163], v[180:183], 0
	v_mfma_f32_16x16x32_bf16 v[116:119], v[172:175], v[180:183], 0
	v_mfma_f32_16x16x32_bf16 v[108:111], v[160:163], v[188:191], 0
	v_mfma_f32_16x16x32_bf16 v[100:103], v[172:175], v[188:191], 0
	v_mfma_f32_16x16x32_bf16 v[92:95], v[160:163], v[202:205], 0
	v_mfma_f32_16x16x32_bf16 v[84:87], v[172:175], v[202:205], 0
	v_mfma_f32_16x16x32_bf16 v[76:79], v[160:163], v[210:213], 0
	v_mfma_f32_16x16x32_bf16 v[68:71], v[172:175], v[210:213], 0
	v_mfma_f32_16x16x32_bf16 v[124:127], v[168:171], v[184:187], v[124:127]
	v_mfma_f32_16x16x32_bf16 v[116:119], v[176:179], v[184:187], v[116:119]
	v_mfma_f32_16x16x32_bf16 v[108:111], v[168:171], v[192:195], v[108:111]
	v_mfma_f32_16x16x32_bf16 v[100:103], v[176:179], v[192:195], v[100:103]
	v_mfma_f32_16x16x32_bf16 v[92:95], v[168:171], v[206:209], v[92:95]
	v_mfma_f32_16x16x32_bf16 v[84:87], v[176:179], v[206:209], v[84:87]
	v_mfma_f32_16x16x32_bf16 v[76:79], v[168:171], v[214:217], v[76:79]
	v_mfma_f32_16x16x32_bf16 v[68:71], v[176:179], v[214:217], v[68:71]
	s_setprio 0
	s_barrier
	v_lshl_add_u64 v[198:199], s[24:25], 0, v[134:135]
	s_add_i32 m0, s35, 0x10000
	ds_read_b128 v[180:183], v166 offset:16384
	ds_read_b128 v[184:187], v166 offset:17408
	ds_read_b128 v[188:191], v166 offset:18432
	ds_read_b128 v[192:195], v166 offset:19456
	ds_read_b128 v[202:205], v166 offset:20480
	ds_read_b128 v[206:209], v166 offset:21504
	ds_read_b128 v[210:213], v166 offset:22528
	ds_read_b128 v[214:217], v166 offset:23552
	global_load_lds_dwordx4 v[198:199], off
	s_add_i32 m0, s35, 0x12000
	s_add_u32 s48, s24, 0x40000
	v_lshl_add_u64 v[218:219], s[24:25], 0, v[0:1]
	s_addc_u32 s49, s25, 0
	global_load_lds_dwordx4 v[218:219], off
	v_lshl_add_u64 v[244:245], s[48:49], 0, v[134:135]
	s_add_i32 m0, s35, 0x14000
	v_lshl_add_u64 v[222:223], s[26:27], 0, v[132:133]
	global_load_lds_dwordx4 v[244:245], off
	s_add_i32 m0, s35, 0x16000
	v_lshl_add_u64 v[246:247], s[48:49], 0, v[0:1]
	global_load_lds_dwordx4 v[246:247], off
	v_lshl_add_u64 v[220:221], s[26:27], 0, v[136:137]
	s_waitcnt vmcnt(6) lgkmcnt(0)
	s_barrier
; #define PG8_STAGE(bufoff, gbase, voff) do { _Pragma("unroll") for (int _i = 0; _i < 2; ++_i) \
;         __builtin_amdgcn_global_load_lds((const unsigned*)((const char*)(gbase) + (voff)[_i]), (PG8_LAS unsigned*)(lds + (bufoff) + ldsw + _i * 8192), 16, 0, 0); } while (0)
; #define PG8_LDA(dst, b, h) do { _Pragma("unroll") for (int m = 0; m < 4; ++m) _Pragma("unroll") for (int k = 0; k < 2; ++k) dst[m][k] = *(const PG8_LAS bf16x8*)(lds + PG8_SA(b, h) + aoff + m * 2048 + k * 1024); } while (0)
; #define PG8_LDB(dst, b, h) do { _Pragma("unroll") for (int n = 0; n < 2; ++n) _Pragma("unroll") for (int k = 0; k < 2; ++k) dst[n][k] = *(const PG8_LAS bf16x8*)(lds + PG8_SB(b, h) + boff + n * 2048 + k * 1024); } while (0)
; #define PG8_MMA(ai, bj, At, Bt) do { __builtin_amdgcn_s_setprio(1); _Pragma("unroll") for (int m = 0; m < 4; ++m) _Pragma("unroll") for (int n = 0; n < 2; ++n) _Pragma("unroll") for (int k = 0; k < 2; ++k) \
;         acc[ai][bj][m][n] = __builtin_amdgcn_mfma_f32_16x16x32_bf16(Bt[n][k], At[m][k], acc[ai][bj][m][n], 0, 0, 0); __builtin_amdgcn_s_setprio(0); } while (0)
; #define PG8_WAIT_V(n) asm volatile("s_waitcnt vmcnt(" #n ")" ::: "memory")
; #define PG8_WAIT_L(n) asm volatile("s_waitcnt lgkmcnt(" #n ")" ::: "memory")
; #define PG8_BAR __builtin_amdgcn_s_barrier()
; template <class Epi, class Sched, bool ALIGN_EPI = false, bool SP2 = false>
; __device__ __forceinline__ void gemm_phase(PG8_LAS unsigned char* lds, const Gemm g, const Sched& S, const Epi& E) {
;     ...
;             const char* a1 = cA + (size_t)(t + 1) * kstep;
;             const char* a2 = last ? nA : cA + (size_t)(t + 2) * kstep; const char* b2 = last ? nB : cB + (size_t)(t + 2) * kstep;
;             const char* a3 = a2 + kstep; const char* b3 = b2 + kstep;
;             if (last && has_next) S.a_ready(nxt);
;             if constexpr (SP2) {
;             PG8_LDB(B0, 0, 0); PG8_LDB(B1, 0, 1); PG8_SCHED; PG8_LDA(At, 0, 0); PG8_STAGE(PG8_SA(1, 1), a1 + hstep, voffA);
;             PG8_WAIT_V(8); PG8_WAIT_L(0); PG8_BAR; PG8_MMA(0, 0, At, B0); PG8_MMA(0, 1, At, B1); PG8_BAR; PG8_SCHED;
;             PG8_LDA(At, 0, 1); PG8_STAGE(PG8_SB(0, 0), b2, voffB); PG8_STAGE(PG8_SB(0, 1), b2 + hstep, voffB); PG8_STAGE(PG8_SA(0, 0), a2, voffA);
;             PG8_WAIT_V(8); PG8_WAIT_L(0); PG8_BAR; PG8_MMA(1, 0, At, B0); PG8_MMA(1, 1, At, B1); PG8_BAR; PG8_SCHED;
	s_setprio 1
	v_mfma_f32_16x16x32_bf16 v[64:67], v[144:147], v[180:183], 0
	v_mfma_f32_16x16x32_bf16 v[56:59], v[152:155], v[180:183], 0
	v_mfma_f32_16x16x32_bf16 v[48:51], v[144:147], v[188:191], 0
	v_mfma_f32_16x16x32_bf16 v[40:43], v[152:155], v[188:191], 0
	v_mfma_f32_16x16x32_bf16 v[32:35], v[144:147], v[202:205], 0
	v_mfma_f32_16x16x32_bf16 v[24:27], v[152:155], v[202:205], 0
	v_mfma_f32_16x16x32_bf16 v[16:19], v[144:147], v[210:213], 0
	v_mfma_f32_16x16x32_bf16 v[8:11], v[152:155], v[210:213], 0
	v_mfma_f32_16x16x32_bf16 v[64:67], v[148:151], v[184:187], v[64:67]
	v_mfma_f32_16x16x32_bf16 v[56:59], v[156:159], v[184:187], v[56:59]
	v_mfma_f32_16x16x32_bf16 v[48:51], v[148:151], v[192:195], v[48:51]
	v_mfma_f32_16x16x32_bf16 v[40:43], v[156:159], v[192:195], v[40:43]
	v_mfma_f32_16x16x32_bf16 v[32:35], v[148:151], v[206:209], v[32:35]
	v_mfma_f32_16x16x32_bf16 v[24:27], v[156:159], v[206:209], v[24:27]
	v_mfma_f32_16x16x32_bf16 v[16:19], v[148:151], v[214:217], v[16:19]
	v_mfma_f32_16x16x32_bf16 v[8:11], v[156:159], v[214:217], v[8:11]
	s_setprio 0
	s_setprio 1
	v_mfma_f32_16x16x32_bf16 v[60:63], v[160:163], v[180:183], 0
	v_mfma_f32_16x16x32_bf16 v[52:55], v[172:175], v[180:183], 0
	v_mfma_f32_16x16x32_bf16 v[44:47], v[160:163], v[188:191], 0
	v_mfma_f32_16x16x32_bf16 v[36:39], v[172:175], v[188:191], 0
	v_mfma_f32_16x16x32_bf16 v[28:31], v[160:163], v[202:205], 0
	v_mfma_f32_16x16x32_bf16 v[20:23], v[172:175], v[202:205], 0
	v_mfma_f32_16x16x32_bf16 v[12:15], v[160:163], v[210:213], 0
	v_mfma_f32_16x16x32_bf16 v[4:7], v[172:175], v[210:213], 0
	v_mfma_f32_16x16x32_bf16 v[60:63], v[168:171], v[184:187], v[60:63]
	v_mfma_f32_16x16x32_bf16 v[52:55], v[176:179], v[184:187], v[52:55]
	v_mfma_f32_16x16x32_bf16 v[44:47], v[168:171], v[192:195], v[44:47]
	v_mfma_f32_16x16x32_bf16 v[36:39], v[176:179], v[192:195], v[36:39]
	v_mfma_f32_16x16x32_bf16 v[28:31], v[168:171], v[206:209], v[28:31]
	v_mfma_f32_16x16x32_bf16 v[20:23], v[176:179], v[206:209], v[20:23]
	v_mfma_f32_16x16x32_bf16 v[12:15], v[168:171], v[214:217], v[12:15]
	v_mfma_f32_16x16x32_bf16 v[4:7], v[176:179], v[214:217], v[4:7]
	s_setprio 0
	s_barrier
	s_branch .Lkmid_2
.LBB0_405:
	s_add_u32 s24, s8, 0xfffc0080
	s_addc_u32 s25, s9, -1
	s_cmp_eq_u32 s46, 12
	s_cselect_b32 s27, s7, s25
	s_cselect_b32 s26, s17, s24
	s_cselect_b32 s25, s19, s45
	s_cselect_b32 s24, s43, s44
	s_add_i32 m0, s41, 0xffffff80
	s_add_i32 s50, 0, 0x14000
	ds_read_b128 v[144:147], v164
	ds_read_b128 v[148:151], v164 offset:1024
	ds_read_b128 v[152:155], v164 offset:2048
	ds_read_b128 v[156:159], v164 offset:3072
	ds_read_b128 v[160:163], v164 offset:16384
	ds_read_b128 v[168:171], v164 offset:17408
	ds_read_b128 v[172:175], v164 offset:18432
	ds_read_b128 v[176:179], v164 offset:19456
	global_load_lds_dwordx4 v[220:221], off offset:128
	s_add_i32 m0, s42, 0xffffff80
	v_lshl_add_u64 v[198:199], s[8:9], 0, v[140:141]
	global_load_lds_dwordx4 v[222:223], off offset:128
	s_add_i32 m0, s37, 0xc000
	ds_read_b128 v[180:183], v166
	ds_read_b128 v[184:187], v166 offset:1024
	ds_read_b128 v[188:191], v166 offset:2048
	ds_read_b128 v[192:195], v166 offset:3072
	ds_read_b128 v[202:205], v166 offset:4096
	ds_read_b128 v[206:209], v166 offset:5120
	ds_read_b128 v[210:213], v166 offset:6144
	ds_read_b128 v[214:217], v166 offset:7168
	global_load_lds_dwordx4 v[198:199], off
	s_add_i32 m0, s37, 0xe000
	v_lshl_add_u64 v[198:199], s[8:9], 0, v[142:143]
	global_load_lds_dwordx4 v[198:199], off
	s_waitcnt vmcnt(8) lgkmcnt(0)
	s_barrier
	s_setprio 1
	v_mfma_f32_16x16x32_bf16 v[128:131], v[144:147], v[180:183], v[128:131]
	v_mfma_f32_16x16x32_bf16 v[120:123], v[152:155], v[180:183], v[120:123]
	v_mfma_f32_16x16x32_bf16 v[112:115], v[144:147], v[188:191], v[112:115]
	v_mfma_f32_16x16x32_bf16 v[104:107], v[152:155], v[188:191], v[104:107]
	v_mfma_f32_16x16x32_bf16 v[96:99], v[144:147], v[202:205], v[96:99]
	v_mfma_f32_16x16x32_bf16 v[88:91], v[152:155], v[202:205], v[88:91]
	v_mfma_f32_16x16x32_bf16 v[80:83], v[144:147], v[210:213], v[80:83]
	v_mfma_f32_16x16x32_bf16 v[72:75], v[152:155], v[210:213], v[72:75]
	v_mfma_f32_16x16x32_bf16 v[128:131], v[148:151], v[184:187], v[128:131]
	v_mfma_f32_16x16x32_bf16 v[120:123], v[156:159], v[184:187], v[120:123]
	v_mfma_f32_16x16x32_bf16 v[112:115], v[148:151], v[192:195], v[112:115]
	v_mfma_f32_16x16x32_bf16 v[104:107], v[156:159], v[192:195], v[104:107]
	v_mfma_f32_16x16x32_bf16 v[96:99], v[148:151], v[206:209], v[96:99]
	v_mfma_f32_16x16x32_bf16 v[88:91], v[156:159], v[206:209], v[88:91]
	v_mfma_f32_16x16x32_bf16 v[80:83], v[148:151], v[214:217], v[80:83]
	v_mfma_f32_16x16x32_bf16 v[72:75], v[156:159], v[214:217], v[72:75]
	s_setprio 0
	s_setprio 1
	v_mfma_f32_16x16x32_bf16 v[124:127], v[160:163], v[180:183], v[124:127]
	v_mfma_f32_16x16x32_bf16 v[116:119], v[172:175], v[180:183], v[116:119]
	v_mfma_f32_16x16x32_bf16 v[108:111], v[160:163], v[188:191], v[108:111]
	v_mfma_f32_16x16x32_bf16 v[100:103], v[172:175], v[188:191], v[100:103]
	v_mfma_f32_16x16x32_bf16 v[92:95], v[160:163], v[202:205], v[92:95]
	v_mfma_f32_16x16x32_bf16 v[84:87], v[172:175], v[202:205], v[84:87]
	v_mfma_f32_16x16x32_bf16 v[76:79], v[160:163], v[210:213], v[76:79]
	v_mfma_f32_16x16x32_bf16 v[68:71], v[172:175], v[210:213], v[68:71]
	v_mfma_f32_16x16x32_bf16 v[124:127], v[168:171], v[184:187], v[124:127]
	v_mfma_f32_16x16x32_bf16 v[116:119], v[176:179], v[184:187], v[116:119]
	v_mfma_f32_16x16x32_bf16 v[108:111], v[168:171], v[192:195], v[108:111]
	v_mfma_f32_16x16x32_bf16 v[100:103], v[176:179], v[192:195], v[100:103]
	v_mfma_f32_16x16x32_bf16 v[92:95], v[168:171], v[206:209], v[92:95]
	v_mfma_f32_16x16x32_bf16 v[84:87], v[176:179], v[206:209], v[84:87]
	v_mfma_f32_16x16x32_bf16 v[76:79], v[168:171], v[214:217], v[76:79]
	v_mfma_f32_16x16x32_bf16 v[68:71], v[176:179], v[214:217], v[68:71]
	s_setprio 0
	s_barrier
; #define PG8_STAGE(bufoff, gbase, voff) do { _Pragma("unroll") for (int _i = 0; _i < 2; ++_i) \
;         __builtin_amdgcn_global_load_lds((const unsigned*)((const char*)(gbase) + (voff)[_i]), (PG8_LAS unsigned*)(lds + (bufoff) + ldsw + _i * 8192), 16, 0, 0); } while (0)
; #define PG8_LDA(dst, b, h) do { _Pragma("unroll") for (int m = 0; m < 4; ++m) _Pragma("unroll") for (int k = 0; k < 2; ++k) dst[m][k] = *(const PG8_LAS bf16x8*)(lds + PG8_SA(b, h) + aoff + m * 2048 + k * 1024); } while (0)
; #define PG8_MMA(ai, bj, At, Bt) do { __builtin_amdgcn_s_setprio(1); _Pragma("unroll") for (int m = 0; m < 4; ++m) _Pragma("unroll") for (int n = 0; n < 2; ++n) _Pragma("unroll") for (int k = 0; k < 2; ++k) \
;         acc[ai][bj][m][n] = __builtin_amdgcn_mfma_f32_16x16x32_bf16(Bt[n][k], At[m][k], acc[ai][bj][m][n], 0, 0, 0); __builtin_amdgcn_s_setprio(0); } while (0)
; #define PG8_WAIT_V(n) asm volatile("s_waitcnt vmcnt(" #n ")" ::: "memory")
; #define PG8_WAIT_L(n) asm volatile("s_waitcnt lgkmcnt(" #n ")" ::: "memory")
; #define PG8_BAR __builtin_amdgcn_s_barrier()
; #define PG8_SCHED __builtin_amdgcn_sched_barrier(0)
; template <class Epi, class Sched, bool ALIGN_EPI = false, bool SP2 = false>
; __device__ __forceinline__ void gemm_phase(PG8_LAS unsigned char* lds, const Gemm g, const Sched& S, const Epi& E) {
;     ...
;             PG8_LDA(At, 0, 1); PG8_STAGE(PG8_SB(0, 0), b2, voffB); PG8_STAGE(PG8_SB(0, 1), b2 + hstep, voffB); PG8_STAGE(PG8_SA(0, 0), a2, voffA);
;             PG8_WAIT_V(8); PG8_WAIT_L(0); PG8_BAR; PG8_MMA(1, 0, At, B0); PG8_MMA(1, 1, At, B1); PG8_BAR; PG8_SCHED;
	v_lshl_add_u64 v[198:199], s[24:25], 0, v[134:135]
	s_add_i32 m0, s35, 0x10000
	ds_read_b128 v[180:183], v166 offset:16384
	ds_read_b128 v[184:187], v166 offset:17408
	ds_read_b128 v[188:191], v166 offset:18432
	ds_read_b128 v[192:195], v166 offset:19456
	ds_read_b128 v[202:205], v166 offset:20480
	ds_read_b128 v[206:209], v166 offset:21504
	ds_read_b128 v[210:213], v166 offset:22528
	ds_read_b128 v[214:217], v166 offset:23552
	global_load_lds_dwordx4 v[198:199], off
	s_add_i32 m0, s35, 0x12000
	s_add_u32 s48, s24, 0x40000
	v_lshl_add_u64 v[218:219], s[24:25], 0, v[0:1]
	s_addc_u32 s49, s25, 0
	global_load_lds_dwordx4 v[218:219], off
	v_lshl_add_u64 v[244:245], s[48:49], 0, v[134:135]
	s_add_i32 m0, s35, 0x14000
	v_lshl_add_u64 v[222:223], s[26:27], 0, v[132:133]
	global_load_lds_dwordx4 v[244:245], off
	s_add_i32 m0, s35, 0x16000
	v_lshl_add_u64 v[246:247], s[48:49], 0, v[0:1]
	global_load_lds_dwordx4 v[246:247], off
	v_lshl_add_u64 v[220:221], s[26:27], 0, v[136:137]
	s_waitcnt vmcnt(6) lgkmcnt(0)
	s_barrier
	s_setprio 1
	v_mfma_f32_16x16x32_bf16 v[64:67], v[144:147], v[180:183], v[64:67]
	v_mfma_f32_16x16x32_bf16 v[56:59], v[152:155], v[180:183], v[56:59]
	v_mfma_f32_16x16x32_bf16 v[48:51], v[144:147], v[188:191], v[48:51]
	v_mfma_f32_16x16x32_bf16 v[40:43], v[152:155], v[188:191], v[40:43]
	v_mfma_f32_16x16x32_bf16 v[32:35], v[144:147], v[202:205], v[32:35]
	v_mfma_f32_16x16x32_bf16 v[24:27], v[152:155], v[202:205], v[24:27]
	v_mfma_f32_16x16x32_bf16 v[16:19], v[144:147], v[210:213], v[16:19]
	v_mfma_f32_16x16x32_bf16 v[8:11], v[152:155], v[210:213], v[8:11]
	v_mfma_f32_16x16x32_bf16 v[64:67], v[148:151], v[184:187], v[64:67]
	v_mfma_f32_16x16x32_bf16 v[56:59], v[156:159], v[184:187], v[56:59]
	v_mfma_f32_16x16x32_bf16 v[48:51], v[148:151], v[192:195], v[48:51]
	v_mfma_f32_16x16x32_bf16 v[40:43], v[156:159], v[192:195], v[40:43]
	v_mfma_f32_16x16x32_bf16 v[32:35], v[148:151], v[206:209], v[32:35]
	v_mfma_f32_16x16x32_bf16 v[24:27], v[156:159], v[206:209], v[24:27]
	v_mfma_f32_16x16x32_bf16 v[16:19], v[148:151], v[214:217], v[16:19]
	v_mfma_f32_16x16x32_bf16 v[8:11], v[156:159], v[214:217], v[8:11]
	s_setprio 0
	s_setprio 1
	v_mfma_f32_16x16x32_bf16 v[60:63], v[160:163], v[180:183], v[60:63]
	v_mfma_f32_16x16x32_bf16 v[52:55], v[172:175], v[180:183], v[52:55]
	v_mfma_f32_16x16x32_bf16 v[44:47], v[160:163], v[188:191], v[44:47]
	v_mfma_f32_16x16x32_bf16 v[36:39], v[172:175], v[188:191], v[36:39]
	v_mfma_f32_16x16x32_bf16 v[28:31], v[160:163], v[202:205], v[28:31]
	v_mfma_f32_16x16x32_bf16 v[20:23], v[172:175], v[202:205], v[20:23]
	v_mfma_f32_16x16x32_bf16 v[12:15], v[160:163], v[210:213], v[12:15]
	v_mfma_f32_16x16x32_bf16 v[4:7], v[172:175], v[210:213], v[4:7]
	v_mfma_f32_16x16x32_bf16 v[60:63], v[168:171], v[184:187], v[60:63]
	v_mfma_f32_16x16x32_bf16 v[52:55], v[176:179], v[184:187], v[52:55]
	v_mfma_f32_16x16x32_bf16 v[44:47], v[168:171], v[192:195], v[44:47]
	v_mfma_f32_16x16x32_bf16 v[36:39], v[176:179], v[192:195], v[36:39]
	v_mfma_f32_16x16x32_bf16 v[28:31], v[168:171], v[206:209], v[28:31]
	v_mfma_f32_16x16x32_bf16 v[20:23], v[176:179], v[206:209], v[20:23]
	v_mfma_f32_16x16x32_bf16 v[12:15], v[168:171], v[214:217], v[12:15]
	v_mfma_f32_16x16x32_bf16 v[4:7], v[176:179], v[214:217], v[4:7]
	s_setprio 0
	s_barrier
; #define PG8_STAGE(bufoff, gbase, voff) do { _Pragma("unroll") for (int _i = 0; _i < 2; ++_i) \
;         __builtin_amdgcn_global_load_lds((const unsigned*)((const char*)(gbase) + (voff)[_i]), (PG8_LAS unsigned*)(lds + (bufoff) + ldsw + _i * 8192), 16, 0, 0); } while (0)
; #define PG8_LDA(dst, b, h) do { _Pragma("unroll") for (int m = 0; m < 4; ++m) _Pragma("unroll") for (int k = 0; k < 2; ++k) dst[m][k] = *(const PG8_LAS bf16x8*)(lds + PG8_SA(b, h) + aoff + m * 2048 + k * 1024); } while (0)
; #define PG8_LDB(dst, b, h) do { _Pragma("unroll") for (int n = 0; n < 2; ++n) _Pragma("unroll") for (int k = 0; k < 2; ++k) dst[n][k] = *(const PG8_LAS bf16x8*)(lds + PG8_SB(b, h) + boff + n * 2048 + k * 1024); } while (0)
; #define PG8_MMA(ai, bj, At, Bt) do { __builtin_amdgcn_s_setprio(1); _Pragma("unroll") for (int m = 0; m < 4; ++m) _Pragma("unroll") for (int n = 0; n < 2; ++n) _Pragma("unroll") for (int k = 0; k < 2; ++k) \
;         acc[ai][bj][m][n] = __builtin_amdgcn_mfma_f32_16x16x32_bf16(Bt[n][k], At[m][k], acc[ai][bj][m][n], 0, 0, 0); __builtin_amdgcn_s_setprio(0); } while (0)
; #define PG8_WAIT_V(n) asm volatile("s_waitcnt vmcnt(" #n ")" ::: "memory")
; #define PG8_WAIT_L(n) asm volatile("s_waitcnt lgkmcnt(" #n ")" ::: "memory")
; #define PG8_BAR __builtin_amdgcn_s_barrier()
; #define PG8_SCHED __builtin_amdgcn_sched_barrier(0)
; template <class Epi, class Sched, bool ALIGN_EPI = false, bool SP2 = false>
; __device__ __forceinline__ void gemm_phase(PG8_LAS unsigned char* lds, const Gemm g, const Sched& S, const Epi& E) {
;     ...
;             PG8_LDB(B0, 1, 0); PG8_LDB(B1, 1, 1); PG8_SCHED; PG8_LDA(At, 1, 0); PG8_STAGE(PG8_SA(0, 1), a2 + hstep, voffA);
;             PG8_WAIT_V(8); PG8_WAIT_L(0); PG8_BAR; PG8_MMA(0, 0, At, B0); PG8_MMA(0, 1, At, B1); PG8_BAR; PG8_SCHED;
;             PG8_LDA(At, 1, 1); PG8_STAGE(PG8_SB(1, 0), b3, voffB); PG8_STAGE(PG8_SB(1, 1), b3 + hstep, voffB); PG8_STAGE(PG8_SA(1, 0), a3, voffA);
;             PG8_WAIT_V(8); PG8_WAIT_L(0); PG8_BAR; PG8_MMA(1, 0, At, B0); PG8_MMA(1, 1, At, B1); PG8_BAR; PG8_SCHED;
.Lkmid_2:
	ds_read_b128 v[144:147], v164 offset:32768
	ds_read_b128 v[148:151], v164 offset:33792
	ds_read_b128 v[152:155], v164 offset:34816
	ds_read_b128 v[156:159], v164 offset:35840
	ds_read_b128 v[160:163], v164 offset:49152
	ds_read_b128 v[168:171], v164 offset:50176
	ds_read_b128 v[172:175], v164 offset:51200
	ds_read_b128 v[176:179], v164 offset:52224
	s_mov_b32 m0, s37
	s_add_u32 s26, s26, 0x40000
	s_addc_u32 s27, s27, 0
	global_load_lds_dwordx4 v[220:221], off
	s_mov_b32 m0, s38
	v_lshl_add_u64 v[224:225], s[26:27], 0, v[136:137]
	global_load_lds_dwordx4 v[222:223], off
	s_mov_b32 m0, s39
	ds_read_b128 v[180:183], v166 offset:32768
	ds_read_b128 v[184:187], v166 offset:33792
	ds_read_b128 v[188:191], v166 offset:34816
	ds_read_b128 v[192:195], v166 offset:35840
	ds_read_b128 v[202:205], v166 offset:36864
	ds_read_b128 v[206:209], v166 offset:37888
	ds_read_b128 v[210:213], v166 offset:38912
	ds_read_b128 v[214:217], v166 offset:39936
	global_load_lds_dwordx4 v[224:225], off
	s_mov_b32 m0, s40
	v_lshl_add_u64 v[224:225], s[26:27], 0, v[132:133]
	global_load_lds_dwordx4 v[224:225], off
	s_waitcnt vmcnt(8) lgkmcnt(0)
	s_barrier
	s_setprio 1
	v_mfma_f32_16x16x32_bf16 v[128:131], v[144:147], v[180:183], v[128:131]
	v_mfma_f32_16x16x32_bf16 v[120:123], v[152:155], v[180:183], v[120:123]
	v_mfma_f32_16x16x32_bf16 v[112:115], v[144:147], v[188:191], v[112:115]
	v_mfma_f32_16x16x32_bf16 v[104:107], v[152:155], v[188:191], v[104:107]
	v_mfma_f32_16x16x32_bf16 v[96:99], v[144:147], v[202:205], v[96:99]
	v_mfma_f32_16x16x32_bf16 v[88:91], v[152:155], v[202:205], v[88:91]
	v_mfma_f32_16x16x32_bf16 v[80:83], v[144:147], v[210:213], v[80:83]
	v_mfma_f32_16x16x32_bf16 v[72:75], v[152:155], v[210:213], v[72:75]
	v_mfma_f32_16x16x32_bf16 v[128:131], v[148:151], v[184:187], v[128:131]
	v_mfma_f32_16x16x32_bf16 v[120:123], v[156:159], v[184:187], v[120:123]
	v_mfma_f32_16x16x32_bf16 v[112:115], v[148:151], v[192:195], v[112:115]
	v_mfma_f32_16x16x32_bf16 v[104:107], v[156:159], v[192:195], v[104:107]
	v_mfma_f32_16x16x32_bf16 v[96:99], v[148:151], v[206:209], v[96:99]
	v_mfma_f32_16x16x32_bf16 v[88:91], v[156:159], v[206:209], v[88:91]
	v_mfma_f32_16x16x32_bf16 v[80:83], v[148:151], v[214:217], v[80:83]
	v_mfma_f32_16x16x32_bf16 v[72:75], v[156:159], v[214:217], v[72:75]
	s_setprio 0
	s_setprio 1
	v_mfma_f32_16x16x32_bf16 v[124:127], v[160:163], v[180:183], v[124:127]
	v_mfma_f32_16x16x32_bf16 v[116:119], v[172:175], v[180:183], v[116:119]
	v_mfma_f32_16x16x32_bf16 v[108:111], v[160:163], v[188:191], v[108:111]
	v_mfma_f32_16x16x32_bf16 v[100:103], v[172:175], v[188:191], v[100:103]
	v_mfma_f32_16x16x32_bf16 v[92:95], v[160:163], v[202:205], v[92:95]
	v_mfma_f32_16x16x32_bf16 v[84:87], v[172:175], v[202:205], v[84:87]
	v_mfma_f32_16x16x32_bf16 v[76:79], v[160:163], v[210:213], v[76:79]
	v_mfma_f32_16x16x32_bf16 v[68:71], v[172:175], v[210:213], v[68:71]
	v_mfma_f32_16x16x32_bf16 v[124:127], v[168:171], v[184:187], v[124:127]
	v_mfma_f32_16x16x32_bf16 v[116:119], v[176:179], v[184:187], v[116:119]
	v_mfma_f32_16x16x32_bf16 v[108:111], v[168:171], v[192:195], v[108:111]
	v_mfma_f32_16x16x32_bf16 v[100:103], v[176:179], v[192:195], v[100:103]
	v_mfma_f32_16x16x32_bf16 v[92:95], v[168:171], v[206:209], v[92:95]
	v_mfma_f32_16x16x32_bf16 v[84:87], v[176:179], v[206:209], v[84:87]
	v_mfma_f32_16x16x32_bf16 v[76:79], v[168:171], v[214:217], v[76:79]
	v_mfma_f32_16x16x32_bf16 v[68:71], v[176:179], v[214:217], v[68:71]
	s_setprio 0
	s_barrier
	s_add_i32 m0, s35, 0x17f80
	ds_read_b128 v[180:183], v166 offset:49152
	ds_read_b128 v[184:187], v166 offset:50176
	ds_read_b128 v[188:191], v166 offset:51200
	ds_read_b128 v[192:195], v166 offset:52224
	ds_read_b128 v[202:205], v166 offset:53248
	ds_read_b128 v[206:209], v166 offset:54272
	ds_read_b128 v[210:213], v166 offset:55296
	ds_read_b128 v[214:217], v166 offset:56320
	global_load_lds_dwordx4 v[198:199], off offset:128
	s_add_i32 m0, s35, 0x19f80
	s_add_u32 s8, s8, 0x100
	s_addc_u32 s9, s9, 0
	global_load_lds_dwordx4 v[218:219], off offset:128
	s_add_i32 m0, s35, 0x1bf80
	s_add_u32 s44, s44, 0x100
	s_addc_u32 s45, s45, 0
	global_load_lds_dwordx4 v[244:245], off offset:128
	s_add_i32 m0, s35, 0x1df80
	s_cmp_eq_u32 s46, 12
	global_load_lds_dwordx4 v[246:247], off offset:128
	s_cbranch_scc0 .Lks4_2
	s_add_i32 m0, s41, 0xffffff80
	s_nop 0
	global_load_lds_dwordx4 v[220:221], off offset:128
	s_add_i32 m0, s42, 0xffffff80
	s_nop 0
	global_load_lds_dwordx4 v[222:223], off offset:128
.Lks4_2:
	s_waitcnt vmcnt(6) lgkmcnt(0)
	s_barrier
	s_setprio 1
	v_mfma_f32_16x16x32_bf16 v[64:67], v[144:147], v[180:183], v[64:67]
	v_mfma_f32_16x16x32_bf16 v[56:59], v[152:155], v[180:183], v[56:59]
	v_mfma_f32_16x16x32_bf16 v[48:51], v[144:147], v[188:191], v[48:51]
	v_mfma_f32_16x16x32_bf16 v[40:43], v[152:155], v[188:191], v[40:43]
	v_mfma_f32_16x16x32_bf16 v[32:35], v[144:147], v[202:205], v[32:35]
	v_mfma_f32_16x16x32_bf16 v[24:27], v[152:155], v[202:205], v[24:27]
	v_mfma_f32_16x16x32_bf16 v[16:19], v[144:147], v[210:213], v[16:19]
	v_mfma_f32_16x16x32_bf16 v[8:11], v[152:155], v[210:213], v[8:11]
	v_mfma_f32_16x16x32_bf16 v[64:67], v[148:151], v[184:187], v[64:67]
	v_mfma_f32_16x16x32_bf16 v[56:59], v[156:159], v[184:187], v[56:59]
	v_mfma_f32_16x16x32_bf16 v[48:51], v[148:151], v[192:195], v[48:51]
	v_mfma_f32_16x16x32_bf16 v[40:43], v[156:159], v[192:195], v[40:43]
	v_mfma_f32_16x16x32_bf16 v[32:35], v[148:151], v[206:209], v[32:35]
	v_mfma_f32_16x16x32_bf16 v[24:27], v[156:159], v[206:209], v[24:27]
	v_mfma_f32_16x16x32_bf16 v[16:19], v[148:151], v[214:217], v[16:19]
	v_mfma_f32_16x16x32_bf16 v[8:11], v[156:159], v[214:217], v[8:11]
	s_setprio 0
	s_setprio 1
	v_mfma_f32_16x16x32_bf16 v[60:63], v[160:163], v[180:183], v[60:63]
	v_mfma_f32_16x16x32_bf16 v[52:55], v[172:175], v[180:183], v[52:55]
	v_mfma_f32_16x16x32_bf16 v[44:47], v[160:163], v[188:191], v[44:47]
	v_mfma_f32_16x16x32_bf16 v[36:39], v[172:175], v[188:191], v[36:39]
	v_mfma_f32_16x16x32_bf16 v[28:31], v[160:163], v[202:205], v[28:31]
	v_mfma_f32_16x16x32_bf16 v[20:23], v[172:175], v[202:205], v[20:23]
	v_mfma_f32_16x16x32_bf16 v[12:15], v[160:163], v[210:213], v[12:15]
	v_mfma_f32_16x16x32_bf16 v[4:7], v[172:175], v[210:213], v[4:7]
	v_mfma_f32_16x16x32_bf16 v[60:63], v[168:171], v[184:187], v[60:63]
	v_mfma_f32_16x16x32_bf16 v[52:55], v[176:179], v[184:187], v[52:55]
	v_mfma_f32_16x16x32_bf16 v[44:47], v[168:171], v[192:195], v[44:47]
	v_mfma_f32_16x16x32_bf16 v[36:39], v[176:179], v[192:195], v[36:39]
	v_mfma_f32_16x16x32_bf16 v[28:31], v[168:171], v[206:209], v[28:31]
	v_mfma_f32_16x16x32_bf16 v[20:23], v[176:179], v[206:209], v[20:23]
	v_mfma_f32_16x16x32_bf16 v[12:15], v[168:171], v[214:217], v[12:15]
	v_mfma_f32_16x16x32_bf16 v[4:7], v[176:179], v[214:217], v[4:7]
	s_setprio 0
	s_barrier
	s_add_i32 s46, s46, 2
	s_cmp_gt_u32 s46, 13
	s_cbranch_scc0 .LBB0_405
	s_and_b64 vcc, exec, s[14:15]
	s_cbranch_vccz .LBB0_408
	s_barrier

; #define PG8_STAGE(bufoff, gbase, voff) do { _Pragma("unroll") for (int _i = 0; _i < 2; ++_i) \
;         __builtin_amdgcn_global_load_lds((const unsigned*)((const char*)(gbase) + (voff)[_i]), (PG8_LAS unsigned*)(lds + (bufoff) + ldsw + _i * 8192), 16, 0, 0); } while (0)
; #define PG8_LDA(dst, b, h) do { _Pragma("unroll") for (int m = 0; m < 4; ++m) _Pragma("unroll") for (int k = 0; k < 2; ++k) dst[m][k] = *(const PG8_LAS bf16x8*)(lds + PG8_SA(b, h) + aoff + m * 2048 + k * 1024); } while (0)
; #define PG8_LDB(dst, b, h) do { _Pragma("unroll") for (int n = 0; n < 2; ++n) _Pragma("unroll") for (int k = 0; k < 2; ++k) dst[n][k] = *(const PG8_LAS bf16x8*)(lds + PG8_SB(b, h) + boff + n * 2048 + k * 1024); } while (0)
; #define PG8_WAIT_V(n) asm volatile("s_waitcnt vmcnt(" #n ")" ::: "memory")
; #define PG8_WAIT_L(n) asm volatile("s_waitcnt lgkmcnt(" #n ")" ::: "memory")
; #define PG8_BAR __builtin_amdgcn_s_barrier()
; #define PG8_SCHED __builtin_amdgcn_sched_barrier(0)
; template <class Epi, class Sched, bool ALIGN_EPI = false, bool SP2 = false>
; __device__ __forceinline__ void gemm_phase(PG8_LAS unsigned char* lds, const Gemm g, const Sched& S, const Epi& E) {
;     ...
;         const char* nA = has_next ? (const char*)g.A + (size_t)nxt.pm * tstep : cA; const char* nB = has_next ? (const char*)g.Bt + (size_t)nxt.pn * tstep : cB;
;         for (int t = 0; t < nt; t += 2) {
;             const bool last = (t == nt - 2);
;             const char* a1 = cA + (size_t)(t + 1) * kstep;
;             const char* a2 = last ? nA : cA + (size_t)(t + 2) * kstep; const char* b2 = last ? nB : cB + (size_t)(t + 2) * kstep;
;             const char* a3 = a2 + kstep; const char* b3 = b2 + kstep;
;             if (last && has_next) S.a_ready(nxt);
;             if constexpr (SP2) {
;             PG8_LDB(B0, 0, 0); PG8_LDB(B1, 0, 1); PG8_SCHED; PG8_LDA(At, 0, 0); PG8_STAGE(PG8_SA(1, 1), a1 + hstep, voffA);
;             PG8_WAIT_V(8); PG8_WAIT_L(0); PG8_BAR; PG8_MMA(0, 0, At, B0); PG8_MMA(0, 1, At, B1); PG8_BAR; PG8_SCHED;
;             PG8_LDA(At, 0, 1); PG8_STAGE(PG8_SB(0, 0), b2, voffB); PG8_STAGE(PG8_SB(0, 1), b2 + hstep, voffB); PG8_STAGE(PG8_SA(0, 0), a2, voffA);
;             PG8_WAIT_V(8); PG8_WAIT_L(0); PG8_BAR; PG8_MMA(1, 0, At, B0); PG8_MMA(1, 1, At, B1); PG8_BAR; PG8_SCHED;
.LBB0_479:
	s_add_u32 s44, s28, 0x100
	s_addc_u32 s45, s29, 0
	s_mov_b32 s53, -2
	s_add_u32 s8, s26, 0x100
	s_addc_u32 s9, s27, 0
	s_cmp_eq_u32 s53, 40
	s_cselect_b32 s31, s23, s9
	s_cselect_b32 s30, s22, s8
	s_cselect_b32 s29, s25, s45
	s_cselect_b32 s28, s24, s44
	ds_read_b128 v[68:71], v234
	ds_read_b128 v[80:83], v234 offset:1024
	ds_read_b128 v[92:95], v234 offset:2048
	ds_read_b128 v[100:103], v234 offset:3072
	ds_read_b128 v[112:115], v234 offset:16384
	ds_read_b128 v[120:123], v234 offset:17408
	ds_read_b128 v[132:135], v234 offset:18432
	ds_read_b128 v[144:147], v234 offset:19456
	v_lshl_add_u64 v[198:199], s[26:27], 0, v[204:205]
	s_add_i32 m0, s40, 0xc000
	ds_read_b128 v[156:159], v236
	ds_read_b128 v[168:171], v236 offset:1024
	ds_read_b128 v[172:175], v236 offset:2048
	ds_read_b128 v[176:179], v236 offset:3072
	ds_read_b128 v[180:183], v236 offset:4096
	ds_read_b128 v[184:187], v236 offset:5120
	ds_read_b128 v[188:191], v236 offset:6144
	ds_read_b128 v[208:211], v236 offset:7168
	global_load_lds_dwordx4 v[198:199], off
	s_add_i32 m0, s40, 0xe000
	v_lshl_add_u64 v[198:199], s[26:27], 0, v[206:207]
	global_load_lds_dwordx4 v[198:199], off
	s_waitcnt vmcnt(8) lgkmcnt(0)
	s_barrier
	s_setprio 1
	v_mfma_f32_16x16x32_bf16 v[164:167], v[68:71], v[156:159], 0
	v_mfma_f32_16x16x32_bf16 v[160:163], v[92:95], v[156:159], 0
	v_mfma_f32_16x16x32_bf16 v[140:143], v[68:71], v[172:175], 0
	v_mfma_f32_16x16x32_bf16 v[136:139], v[92:95], v[172:175], 0
	v_mfma_f32_16x16x32_bf16 v[116:119], v[68:71], v[180:183], 0
	v_mfma_f32_16x16x32_bf16 v[108:111], v[92:95], v[180:183], 0
	v_mfma_f32_16x16x32_bf16 v[88:91], v[68:71], v[188:191], 0
	v_mfma_f32_16x16x32_bf16 v[84:87], v[92:95], v[188:191], 0
	v_mfma_f32_16x16x32_bf16 v[164:167], v[80:83], v[168:171], v[164:167]
	v_mfma_f32_16x16x32_bf16 v[160:163], v[100:103], v[168:171], v[160:163]
	v_mfma_f32_16x16x32_bf16 v[140:143], v[80:83], v[176:179], v[140:143]
	v_mfma_f32_16x16x32_bf16 v[136:139], v[100:103], v[176:179], v[136:139]
	v_mfma_f32_16x16x32_bf16 v[116:119], v[80:83], v[184:187], v[116:119]
	v_mfma_f32_16x16x32_bf16 v[108:111], v[100:103], v[184:187], v[108:111]
	v_mfma_f32_16x16x32_bf16 v[88:91], v[80:83], v[208:211], v[88:91]
	v_mfma_f32_16x16x32_bf16 v[84:87], v[100:103], v[208:211], v[84:87]
	s_setprio 0
	s_setprio 1
	v_mfma_f32_16x16x32_bf16 v[152:155], v[112:115], v[156:159], 0
	v_mfma_f32_16x16x32_bf16 v[148:151], v[132:135], v[156:159], 0
	v_mfma_f32_16x16x32_bf16 v[128:131], v[112:115], v[172:175], 0
	v_mfma_f32_16x16x32_bf16 v[124:127], v[132:135], v[172:175], 0
	v_mfma_f32_16x16x32_bf16 v[104:107], v[112:115], v[180:183], 0
	v_mfma_f32_16x16x32_bf16 v[96:99], v[132:135], v[180:183], 0
	v_mfma_f32_16x16x32_bf16 v[76:79], v[112:115], v[188:191], 0
	v_mfma_f32_16x16x32_bf16 v[72:75], v[132:135], v[188:191], 0
	v_mfma_f32_16x16x32_bf16 v[152:155], v[120:123], v[168:171], v[152:155]
	v_mfma_f32_16x16x32_bf16 v[148:151], v[144:147], v[168:171], v[148:151]
	v_mfma_f32_16x16x32_bf16 v[128:131], v[120:123], v[176:179], v[128:131]
	v_mfma_f32_16x16x32_bf16 v[124:127], v[144:147], v[176:179], v[124:127]
	v_mfma_f32_16x16x32_bf16 v[104:107], v[120:123], v[184:187], v[104:107]
	v_mfma_f32_16x16x32_bf16 v[96:99], v[144:147], v[184:187], v[96:99]
	v_mfma_f32_16x16x32_bf16 v[76:79], v[120:123], v[208:211], v[76:79]
	v_mfma_f32_16x16x32_bf16 v[72:75], v[144:147], v[208:211], v[72:75]
	s_setprio 0
	s_barrier
	v_lshl_add_u64 v[198:199], s[28:29], 0, v[192:193]
	s_add_i32 m0, s39, 0x10000
	ds_read_b128 v[156:159], v236 offset:16384
	ds_read_b128 v[168:171], v236 offset:17408
	ds_read_b128 v[172:175], v236 offset:18432
	ds_read_b128 v[176:179], v236 offset:19456
	ds_read_b128 v[180:183], v236 offset:20480
	ds_read_b128 v[184:187], v236 offset:21504
	ds_read_b128 v[188:191], v236 offset:22528
	ds_read_b128 v[208:211], v236 offset:23552
	global_load_lds_dwordx4 v[198:199], off
	s_add_i32 m0, s39, 0x12000
	s_add_u32 s26, s28, 0xb0000
	v_lshl_add_u64 v[212:213], s[28:29], 0, v[202:203]
	s_addc_u32 s27, s29, 0
	global_load_lds_dwordx4 v[212:213], off
	v_lshl_add_u64 v[244:245], s[26:27], 0, v[192:193]
	s_add_i32 m0, s39, 0x14000
	v_lshl_add_u64 v[216:217], s[30:31], 0, v[194:195]
	global_load_lds_dwordx4 v[244:245], off
	s_add_i32 m0, s39, 0x16000
	v_lshl_add_u64 v[246:247], s[26:27], 0, v[202:203]
	global_load_lds_dwordx4 v[246:247], off
	v_lshl_add_u64 v[214:215], s[30:31], 0, v[0:1]
	s_waitcnt vmcnt(6) lgkmcnt(0)
	s_barrier
	s_setprio 1
	v_mfma_f32_16x16x32_bf16 v[64:67], v[68:71], v[156:159], 0
	v_mfma_f32_16x16x32_bf16 v[60:63], v[92:95], v[156:159], 0
	v_mfma_f32_16x16x32_bf16 v[48:51], v[68:71], v[172:175], 0
	v_mfma_f32_16x16x32_bf16 v[44:47], v[92:95], v[172:175], 0
	v_mfma_f32_16x16x32_bf16 v[32:35], v[68:71], v[180:183], 0
	v_mfma_f32_16x16x32_bf16 v[28:31], v[92:95], v[180:183], 0
	v_mfma_f32_16x16x32_bf16 v[16:19], v[68:71], v[188:191], 0
	v_mfma_f32_16x16x32_bf16 v[12:15], v[92:95], v[188:191], 0
	v_mfma_f32_16x16x32_bf16 v[64:67], v[80:83], v[168:171], v[64:67]
	v_mfma_f32_16x16x32_bf16 v[60:63], v[100:103], v[168:171], v[60:63]
	v_mfma_f32_16x16x32_bf16 v[48:51], v[80:83], v[176:179], v[48:51]
	v_mfma_f32_16x16x32_bf16 v[44:47], v[100:103], v[176:179], v[44:47]
	v_mfma_f32_16x16x32_bf16 v[32:35], v[80:83], v[184:187], v[32:35]
	v_mfma_f32_16x16x32_bf16 v[28:31], v[100:103], v[184:187], v[28:31]
	v_mfma_f32_16x16x32_bf16 v[16:19], v[80:83], v[208:211], v[16:19]
	v_mfma_f32_16x16x32_bf16 v[12:15], v[100:103], v[208:211], v[12:15]
	s_setprio 0
	s_setprio 1
	v_mfma_f32_16x16x32_bf16 v[56:59], v[112:115], v[156:159], 0
	v_mfma_f32_16x16x32_bf16 v[52:55], v[132:135], v[156:159], 0
	v_mfma_f32_16x16x32_bf16 v[40:43], v[112:115], v[172:175], 0
	v_mfma_f32_16x16x32_bf16 v[36:39], v[132:135], v[172:175], 0
	v_mfma_f32_16x16x32_bf16 v[24:27], v[112:115], v[180:183], 0
	v_mfma_f32_16x16x32_bf16 v[20:23], v[132:135], v[180:183], 0
	v_mfma_f32_16x16x32_bf16 v[8:11], v[112:115], v[188:191], 0
	v_mfma_f32_16x16x32_bf16 v[4:7], v[132:135], v[188:191], 0
	v_mfma_f32_16x16x32_bf16 v[56:59], v[120:123], v[168:171], v[56:59]
	v_mfma_f32_16x16x32_bf16 v[52:55], v[144:147], v[168:171], v[52:55]
	v_mfma_f32_16x16x32_bf16 v[40:43], v[120:123], v[176:179], v[40:43]
	v_mfma_f32_16x16x32_bf16 v[36:39], v[144:147], v[176:179], v[36:39]
	v_mfma_f32_16x16x32_bf16 v[24:27], v[120:123], v[184:187], v[24:27]
	v_mfma_f32_16x16x32_bf16 v[20:23], v[144:147], v[184:187], v[20:23]
	v_mfma_f32_16x16x32_bf16 v[8:11], v[120:123], v[208:211], v[8:11]
	v_mfma_f32_16x16x32_bf16 v[4:7], v[144:147], v[208:211], v[4:7]
	s_setprio 0
	s_barrier
	s_branch .Lkmid_3
; #define PG8_STAGE(bufoff, gbase, voff) do { _Pragma("unroll") for (int _i = 0; _i < 2; ++_i) \
;         __builtin_amdgcn_global_load_lds((const unsigned*)((const char*)(gbase) + (voff)[_i]), (PG8_LAS unsigned*)(lds + (bufoff) + ldsw + _i * 8192), 16, 0, 0); } while (0)
; #define PG8_LDA(dst, b, h) do { _Pragma("unroll") for (int m = 0; m < 4; ++m) _Pragma("unroll") for (int k = 0; k < 2; ++k) dst[m][k] = *(const PG8_LAS bf16x8*)(lds + PG8_SA(b, h) + aoff + m * 2048 + k * 1024); } while (0)
; #define PG8_LDB(dst, b, h) do { _Pragma("unroll") for (int n = 0; n < 2; ++n) _Pragma("unroll") for (int k = 0; k < 2; ++k) dst[n][k] = *(const PG8_LAS bf16x8*)(lds + PG8_SB(b, h) + boff + n * 2048 + k * 1024); } while (0)
; #define PG8_MMA(ai, bj, At, Bt) do { __builtin_amdgcn_s_setprio(1); _Pragma("unroll") for (int m = 0; m < 4; ++m) _Pragma("unroll") for (int n = 0; n < 2; ++n) _Pragma("unroll") for (int k = 0; k < 2; ++k) \
;         acc[ai][bj][m][n] = __builtin_amdgcn_mfma_f32_16x16x32_bf16(Bt[n][k], At[m][k], acc[ai][bj][m][n], 0, 0, 0); __builtin_amdgcn_s_setprio(0); } while (0)
; #define PG8_WAIT_V(n) asm volatile("s_waitcnt vmcnt(" #n ")" ::: "memory")
; #define PG8_WAIT_L(n) asm volatile("s_waitcnt lgkmcnt(" #n ")" ::: "memory")
; #define PG8_BAR __builtin_amdgcn_s_barrier()
; template <class Epi, class Sched, bool ALIGN_EPI = false, bool SP2 = false>
; __device__ __forceinline__ void gemm_phase(PG8_LAS unsigned char* lds, const Gemm g, const Sched& S, const Epi& E) {
;     ...
;             const char* a1 = cA + (size_t)(t + 1) * kstep;
;             const char* a2 = last ? nA : cA + (size_t)(t + 2) * kstep; const char* b2 = last ? nB : cB + (size_t)(t + 2) * kstep;
;             const char* a3 = a2 + kstep; const char* b3 = b2 + kstep;
;             if (last && has_next) S.a_ready(nxt);
;             if constexpr (SP2) {
;             PG8_LDB(B0, 0, 0); PG8_LDB(B1, 0, 1); PG8_SCHED; PG8_LDA(At, 0, 0); PG8_STAGE(PG8_SA(1, 1), a1 + hstep, voffA);
;             PG8_WAIT_V(8); PG8_WAIT_L(0); PG8_BAR; PG8_MMA(0, 0, At, B0); PG8_MMA(0, 1, At, B1); PG8_BAR; PG8_SCHED;
;             PG8_LDA(At, 0, 1); PG8_STAGE(PG8_SB(0, 0), b2, voffB); PG8_STAGE(PG8_SB(0, 1), b2 + hstep, voffB); PG8_STAGE(PG8_SA(0, 0), a2, voffA);
;             PG8_WAIT_V(8); PG8_WAIT_L(0); PG8_BAR; PG8_MMA(1, 0, At, B0); PG8_MMA(1, 1, At, B1); PG8_BAR; PG8_SCHED;
.LBB0_480:
	s_add_u32 s8, s26, 0x100
	s_addc_u32 s9, s27, 0
	s_cmp_eq_u32 s53, 40
	s_cselect_b32 s31, s23, s9
	s_cselect_b32 s30, s22, s8
	s_cselect_b32 s29, s25, s45
	s_cselect_b32 s28, s24, s44
	s_add_i32 m0, s47, 0xffffff80
	ds_read_b128 v[68:71], v234
	ds_read_b128 v[80:83], v234 offset:1024
	ds_read_b128 v[92:95], v234 offset:2048
	ds_read_b128 v[100:103], v234 offset:3072
	ds_read_b128 v[112:115], v234 offset:16384
	ds_read_b128 v[120:123], v234 offset:17408
	ds_read_b128 v[132:135], v234 offset:18432
	ds_read_b128 v[144:147], v234 offset:19456
	global_load_lds_dwordx4 v[214:215], off offset:128
	s_add_i32 m0, s48, 0xffffff80
	v_lshl_add_u64 v[198:199], s[26:27], 0, v[204:205]
	global_load_lds_dwordx4 v[216:217], off offset:128
	s_add_i32 m0, s40, 0xc000
	ds_read_b128 v[156:159], v236
	ds_read_b128 v[168:171], v236 offset:1024
	ds_read_b128 v[172:175], v236 offset:2048
	ds_read_b128 v[176:179], v236 offset:3072
	ds_read_b128 v[180:183], v236 offset:4096
	ds_read_b128 v[184:187], v236 offset:5120
	ds_read_b128 v[188:191], v236 offset:6144
	ds_read_b128 v[208:211], v236 offset:7168
	global_load_lds_dwordx4 v[198:199], off
	s_add_i32 m0, s40, 0xe000
	v_lshl_add_u64 v[198:199], s[26:27], 0, v[206:207]
	global_load_lds_dwordx4 v[198:199], off
	s_waitcnt vmcnt(8) lgkmcnt(0)
	s_barrier
	s_setprio 1
	v_mfma_f32_16x16x32_bf16 v[164:167], v[68:71], v[156:159], v[164:167]
	v_mfma_f32_16x16x32_bf16 v[160:163], v[92:95], v[156:159], v[160:163]
	v_mfma_f32_16x16x32_bf16 v[140:143], v[68:71], v[172:175], v[140:143]
	v_mfma_f32_16x16x32_bf16 v[136:139], v[92:95], v[172:175], v[136:139]
	v_mfma_f32_16x16x32_bf16 v[116:119], v[68:71], v[180:183], v[116:119]
	v_mfma_f32_16x16x32_bf16 v[108:111], v[92:95], v[180:183], v[108:111]
	v_mfma_f32_16x16x32_bf16 v[88:91], v[68:71], v[188:191], v[88:91]
	v_mfma_f32_16x16x32_bf16 v[84:87], v[92:95], v[188:191], v[84:87]
	v_mfma_f32_16x16x32_bf16 v[164:167], v[80:83], v[168:171], v[164:167]
	v_mfma_f32_16x16x32_bf16 v[160:163], v[100:103], v[168:171], v[160:163]
	v_mfma_f32_16x16x32_bf16 v[140:143], v[80:83], v[176:179], v[140:143]
	v_mfma_f32_16x16x32_bf16 v[136:139], v[100:103], v[176:179], v[136:139]
	v_mfma_f32_16x16x32_bf16 v[116:119], v[80:83], v[184:187], v[116:119]
	v_mfma_f32_16x16x32_bf16 v[108:111], v[100:103], v[184:187], v[108:111]
	v_mfma_f32_16x16x32_bf16 v[88:91], v[80:83], v[208:211], v[88:91]
	v_mfma_f32_16x16x32_bf16 v[84:87], v[100:103], v[208:211], v[84:87]
	s_setprio 0
	s_setprio 1
	v_mfma_f32_16x16x32_bf16 v[152:155], v[112:115], v[156:159], v[152:155]
	v_mfma_f32_16x16x32_bf16 v[148:151], v[132:135], v[156:159], v[148:151]
	v_mfma_f32_16x16x32_bf16 v[128:131], v[112:115], v[172:175], v[128:131]
	v_mfma_f32_16x16x32_bf16 v[124:127], v[132:135], v[172:175], v[124:127]
	v_mfma_f32_16x16x32_bf16 v[104:107], v[112:115], v[180:183], v[104:107]
	v_mfma_f32_16x16x32_bf16 v[96:99], v[132:135], v[180:183], v[96:99]
	v_mfma_f32_16x16x32_bf16 v[76:79], v[112:115], v[188:191], v[76:79]
	v_mfma_f32_16x16x32_bf16 v[72:75], v[132:135], v[188:191], v[72:75]
	v_mfma_f32_16x16x32_bf16 v[152:155], v[120:123], v[168:171], v[152:155]
	v_mfma_f32_16x16x32_bf16 v[148:151], v[144:147], v[168:171], v[148:151]
	v_mfma_f32_16x16x32_bf16 v[128:131], v[120:123], v[176:179], v[128:131]
	v_mfma_f32_16x16x32_bf16 v[124:127], v[144:147], v[176:179], v[124:127]
	v_mfma_f32_16x16x32_bf16 v[104:107], v[120:123], v[184:187], v[104:107]
	v_mfma_f32_16x16x32_bf16 v[96:99], v[144:147], v[184:187], v[96:99]
	v_mfma_f32_16x16x32_bf16 v[76:79], v[120:123], v[208:211], v[76:79]
	v_mfma_f32_16x16x32_bf16 v[72:75], v[144:147], v[208:211], v[72:75]
	s_setprio 0
	s_barrier
	v_lshl_add_u64 v[198:199], s[28:29], 0, v[192:193]
	s_add_i32 m0, s39, 0x10000
	ds_read_b128 v[156:159], v236 offset:16384
	ds_read_b128 v[168:171], v236 offset:17408
	ds_read_b128 v[172:175], v236 offset:18432
	ds_read_b128 v[176:179], v236 offset:19456
	ds_read_b128 v[180:183], v236 offset:20480
	ds_read_b128 v[184:187], v236 offset:21504
	ds_read_b128 v[188:191], v236 offset:22528
	ds_read_b128 v[208:211], v236 offset:23552
	global_load_lds_dwordx4 v[198:199], off
	s_add_i32 m0, s39, 0x12000
	s_add_u32 s26, s28, 0xb0000
	v_lshl_add_u64 v[212:213], s[28:29], 0, v[202:203]
	s_addc_u32 s27, s29, 0
	global_load_lds_dwordx4 v[212:213], off
	v_lshl_add_u64 v[244:245], s[26:27], 0, v[192:193]
	s_add_i32 m0, s39, 0x14000
	v_lshl_add_u64 v[216:217], s[30:31], 0, v[194:195]
	global_load_lds_dwordx4 v[244:245], off
	s_add_i32 m0, s39, 0x16000
	v_lshl_add_u64 v[246:247], s[26:27], 0, v[202:203]
	global_load_lds_dwordx4 v[246:247], off
	v_lshl_add_u64 v[214:215], s[30:31], 0, v[0:1]
	s_waitcnt vmcnt(6) lgkmcnt(0)
	s_barrier
	s_setprio 1
	v_mfma_f32_16x16x32_bf16 v[64:67], v[68:71], v[156:159], v[64:67]
	v_mfma_f32_16x16x32_bf16 v[60:63], v[92:95], v[156:159], v[60:63]
	v_mfma_f32_16x16x32_bf16 v[48:51], v[68:71], v[172:175], v[48:51]
	v_mfma_f32_16x16x32_bf16 v[44:47], v[92:95], v[172:175], v[44:47]
	v_mfma_f32_16x16x32_bf16 v[32:35], v[68:71], v[180:183], v[32:35]
	v_mfma_f32_16x16x32_bf16 v[28:31], v[92:95], v[180:183], v[28:31]
	v_mfma_f32_16x16x32_bf16 v[16:19], v[68:71], v[188:191], v[16:19]
	v_mfma_f32_16x16x32_bf16 v[12:15], v[92:95], v[188:191], v[12:15]
	v_mfma_f32_16x16x32_bf16 v[64:67], v[80:83], v[168:171], v[64:67]
	v_mfma_f32_16x16x32_bf16 v[60:63], v[100:103], v[168:171], v[60:63]
	v_mfma_f32_16x16x32_bf16 v[48:51], v[80:83], v[176:179], v[48:51]
	v_mfma_f32_16x16x32_bf16 v[44:47], v[100:103], v[176:179], v[44:47]
	v_mfma_f32_16x16x32_bf16 v[32:35], v[80:83], v[184:187], v[32:35]
	v_mfma_f32_16x16x32_bf16 v[28:31], v[100:103], v[184:187], v[28:31]
	v_mfma_f32_16x16x32_bf16 v[16:19], v[80:83], v[208:211], v[16:19]
	v_mfma_f32_16x16x32_bf16 v[12:15], v[100:103], v[208:211], v[12:15]
	s_setprio 0
	s_setprio 1
	v_mfma_f32_16x16x32_bf16 v[56:59], v[112:115], v[156:159], v[56:59]
	v_mfma_f32_16x16x32_bf16 v[52:55], v[132:135], v[156:159], v[52:55]
	v_mfma_f32_16x16x32_bf16 v[40:43], v[112:115], v[172:175], v[40:43]
	v_mfma_f32_16x16x32_bf16 v[36:39], v[132:135], v[172:175], v[36:39]
	v_mfma_f32_16x16x32_bf16 v[24:27], v[112:115], v[180:183], v[24:27]
	v_mfma_f32_16x16x32_bf16 v[20:23], v[132:135], v[180:183], v[20:23]
	v_mfma_f32_16x16x32_bf16 v[8:11], v[112:115], v[188:191], v[8:11]
	v_mfma_f32_16x16x32_bf16 v[4:7], v[132:135], v[188:191], v[4:7]
	v_mfma_f32_16x16x32_bf16 v[56:59], v[120:123], v[168:171], v[56:59]
	v_mfma_f32_16x16x32_bf16 v[52:55], v[144:147], v[168:171], v[52:55]
	v_mfma_f32_16x16x32_bf16 v[40:43], v[120:123], v[176:179], v[40:43]
	v_mfma_f32_16x16x32_bf16 v[36:39], v[144:147], v[176:179], v[36:39]
	v_mfma_f32_16x16x32_bf16 v[24:27], v[120:123], v[184:187], v[24:27]
	v_mfma_f32_16x16x32_bf16 v[20:23], v[144:147], v[184:187], v[20:23]
	v_mfma_f32_16x16x32_bf16 v[8:11], v[120:123], v[208:211], v[8:11]
	v_mfma_f32_16x16x32_bf16 v[4:7], v[144:147], v[208:211], v[4:7]
	s_setprio 0
	s_barrier
; #define PG8_STAGE(bufoff, gbase, voff) do { _Pragma("unroll") for (int _i = 0; _i < 2; ++_i) \
;         __builtin_amdgcn_global_load_lds((const unsigned*)((const char*)(gbase) + (voff)[_i]), (PG8_LAS unsigned*)(lds + (bufoff) + ldsw + _i * 8192), 16, 0, 0); } while (0)
; #define PG8_LDA(dst, b, h) do { _Pragma("unroll") for (int m = 0; m < 4; ++m) _Pragma("unroll") for (int k = 0; k < 2; ++k) dst[m][k] = *(const PG8_LAS bf16x8*)(lds + PG8_SA(b, h) + aoff + m * 2048 + k * 1024); } while (0)
; #define PG8_LDB(dst, b, h) do { _Pragma("unroll") for (int n = 0; n < 2; ++n) _Pragma("unroll") for (int k = 0; k < 2; ++k) dst[n][k] = *(const PG8_LAS bf16x8*)(lds + PG8_SB(b, h) + boff + n * 2048 + k * 1024); } while (0)
; #define PG8_MMA(ai, bj, At, Bt) do { __builtin_amdgcn_s_setprio(1); _Pragma("unroll") for (int m = 0; m < 4; ++m) _Pragma("unroll") for (int n = 0; n < 2; ++n) _Pragma("unroll") for (int k = 0; k < 2; ++k) \
;         acc[ai][bj][m][n] = __builtin_amdgcn_mfma_f32_16x16x32_bf16(Bt[n][k], At[m][k], acc[ai][bj][m][n], 0, 0, 0); __builtin_amdgcn_s_setprio(0); } while (0)
; #define PG8_WAIT_V(n) asm volatile("s_waitcnt vmcnt(" #n ")" ::: "memory")
; #define PG8_WAIT_L(n) asm volatile("s_waitcnt lgkmcnt(" #n ")" ::: "memory")
; #define PG8_BAR __builtin_amdgcn_s_barrier()
; #define PG8_SCHED __builtin_amdgcn_sched_barrier(0)
; template <class Epi, class Sched, bool ALIGN_EPI = false, bool SP2 = false>
; __device__ __forceinline__ void gemm_phase(PG8_LAS unsigned char* lds, const Gemm g, const Sched& S, const Epi& E) {
;     ...
;             PG8_LDB(B0, 1, 0); PG8_LDB(B1, 1, 1); PG8_SCHED; PG8_LDA(At, 1, 0); PG8_STAGE(PG8_SA(0, 1), a2 + hstep, voffA);
;             PG8_WAIT_V(8); PG8_WAIT_L(0); PG8_BAR; PG8_MMA(0, 0, At, B0); PG8_MMA(0, 1, At, B1); PG8_BAR; PG8_SCHED;
;             PG8_LDA(At, 1, 1); PG8_STAGE(PG8_SB(1, 0), b3, voffB); PG8_STAGE(PG8_SB(1, 1), b3 + hstep, voffB); PG8_STAGE(PG8_SA(1, 0), a3, voffA);
;             PG8_WAIT_V(8); PG8_WAIT_L(0); PG8_BAR; PG8_MMA(1, 0, At, B0); PG8_MMA(1, 1, At, B1); PG8_BAR; PG8_SCHED;
.Lkmid_3:
	ds_read_b128 v[68:71], v234 offset:32768
	ds_read_b128 v[80:83], v234 offset:33792
	ds_read_b128 v[92:95], v234 offset:34816
	ds_read_b128 v[100:103], v234 offset:35840
	ds_read_b128 v[112:115], v234 offset:49152
	ds_read_b128 v[120:123], v234 offset:50176
	ds_read_b128 v[132:135], v234 offset:51200
	ds_read_b128 v[144:147], v234 offset:52224
	s_mov_b32 m0, s40
	s_add_u32 s26, s30, 0xb0000
	s_addc_u32 s27, s31, 0
	global_load_lds_dwordx4 v[214:215], off
	s_mov_b32 m0, s41
	v_lshl_add_u64 v[218:219], s[26:27], 0, v[0:1]
	global_load_lds_dwordx4 v[216:217], off
	s_mov_b32 m0, s42
	ds_read_b128 v[156:159], v236 offset:32768
	ds_read_b128 v[168:171], v236 offset:33792
	ds_read_b128 v[172:175], v236 offset:34816
	ds_read_b128 v[176:179], v236 offset:35840
	ds_read_b128 v[180:183], v236 offset:36864
	ds_read_b128 v[184:187], v236 offset:37888
	ds_read_b128 v[188:191], v236 offset:38912
	ds_read_b128 v[208:211], v236 offset:39936
	global_load_lds_dwordx4 v[218:219], off
	s_mov_b32 m0, s43
	v_lshl_add_u64 v[218:219], s[26:27], 0, v[194:195]
	global_load_lds_dwordx4 v[218:219], off
	s_waitcnt vmcnt(8) lgkmcnt(0)
	s_barrier
	s_setprio 1
	v_mfma_f32_16x16x32_bf16 v[164:167], v[68:71], v[156:159], v[164:167]
	v_mfma_f32_16x16x32_bf16 v[160:163], v[92:95], v[156:159], v[160:163]
	v_mfma_f32_16x16x32_bf16 v[140:143], v[68:71], v[172:175], v[140:143]
	v_mfma_f32_16x16x32_bf16 v[136:139], v[92:95], v[172:175], v[136:139]
	v_mfma_f32_16x16x32_bf16 v[116:119], v[68:71], v[180:183], v[116:119]
	v_mfma_f32_16x16x32_bf16 v[108:111], v[92:95], v[180:183], v[108:111]
	v_mfma_f32_16x16x32_bf16 v[88:91], v[68:71], v[188:191], v[88:91]
	v_mfma_f32_16x16x32_bf16 v[84:87], v[92:95], v[188:191], v[84:87]
	v_mfma_f32_16x16x32_bf16 v[164:167], v[80:83], v[168:171], v[164:167]
	v_mfma_f32_16x16x32_bf16 v[160:163], v[100:103], v[168:171], v[160:163]
	v_mfma_f32_16x16x32_bf16 v[140:143], v[80:83], v[176:179], v[140:143]
	v_mfma_f32_16x16x32_bf16 v[136:139], v[100:103], v[176:179], v[136:139]
	v_mfma_f32_16x16x32_bf16 v[116:119], v[80:83], v[184:187], v[116:119]
	v_mfma_f32_16x16x32_bf16 v[108:111], v[100:103], v[184:187], v[108:111]
	v_mfma_f32_16x16x32_bf16 v[88:91], v[80:83], v[208:211], v[88:91]
	v_mfma_f32_16x16x32_bf16 v[84:87], v[100:103], v[208:211], v[84:87]
	s_setprio 0
	s_setprio 1
	v_mfma_f32_16x16x32_bf16 v[152:155], v[112:115], v[156:159], v[152:155]
	v_mfma_f32_16x16x32_bf16 v[148:151], v[132:135], v[156:159], v[148:151]
	v_mfma_f32_16x16x32_bf16 v[128:131], v[112:115], v[172:175], v[128:131]
	v_mfma_f32_16x16x32_bf16 v[124:127], v[132:135], v[172:175], v[124:127]
	v_mfma_f32_16x16x32_bf16 v[104:107], v[112:115], v[180:183], v[104:107]
	v_mfma_f32_16x16x32_bf16 v[96:99], v[132:135], v[180:183], v[96:99]
	v_mfma_f32_16x16x32_bf16 v[76:79], v[112:115], v[188:191], v[76:79]
	v_mfma_f32_16x16x32_bf16 v[72:75], v[132:135], v[188:191], v[72:75]
	v_mfma_f32_16x16x32_bf16 v[152:155], v[120:123], v[168:171], v[152:155]
	v_mfma_f32_16x16x32_bf16 v[148:151], v[144:147], v[168:171], v[148:151]
	v_mfma_f32_16x16x32_bf16 v[128:131], v[120:123], v[176:179], v[128:131]
	v_mfma_f32_16x16x32_bf16 v[124:127], v[144:147], v[176:179], v[124:127]
	v_mfma_f32_16x16x32_bf16 v[104:107], v[120:123], v[184:187], v[104:107]
	v_mfma_f32_16x16x32_bf16 v[96:99], v[144:147], v[184:187], v[96:99]
	v_mfma_f32_16x16x32_bf16 v[76:79], v[120:123], v[208:211], v[76:79]
	v_mfma_f32_16x16x32_bf16 v[72:75], v[144:147], v[208:211], v[72:75]
	s_setprio 0
	s_barrier
	s_add_i32 m0, s39, 0x17f80
	ds_read_b128 v[156:159], v236 offset:49152
	ds_read_b128 v[168:171], v236 offset:50176
	ds_read_b128 v[172:175], v236 offset:51200
	ds_read_b128 v[176:179], v236 offset:52224
	ds_read_b128 v[180:183], v236 offset:53248
	ds_read_b128 v[184:187], v236 offset:54272
	ds_read_b128 v[188:191], v236 offset:55296
	ds_read_b128 v[208:211], v236 offset:56320
	global_load_lds_dwordx4 v[198:199], off offset:128
	s_add_i32 m0, s39, 0x19f80
	s_mov_b64 s[26:27], s[8:9]
	global_load_lds_dwordx4 v[212:213], off offset:128
	s_add_i32 m0, s39, 0x1bf80
	s_add_u32 s44, s44, 0x100
	s_addc_u32 s45, s45, 0
	global_load_lds_dwordx4 v[244:245], off offset:128
	s_add_i32 m0, s39, 0x1df80
	s_cmp_eq_u32 s53, 40
	global_load_lds_dwordx4 v[246:247], off offset:128
	s_cbranch_scc0 .Lks4_3
	s_add_i32 m0, s47, 0xffffff80
	s_nop 0
	global_load_lds_dwordx4 v[214:215], off offset:128
	s_add_i32 m0, s48, 0xffffff80
	s_nop 0
	global_load_lds_dwordx4 v[216:217], off offset:128
.Lks4_3:
	s_waitcnt vmcnt(6) lgkmcnt(0)
	s_barrier
	s_setprio 1
	v_mfma_f32_16x16x32_bf16 v[64:67], v[68:71], v[156:159], v[64:67]
	v_mfma_f32_16x16x32_bf16 v[60:63], v[92:95], v[156:159], v[60:63]
	v_mfma_f32_16x16x32_bf16 v[48:51], v[68:71], v[172:175], v[48:51]
	v_mfma_f32_16x16x32_bf16 v[44:47], v[92:95], v[172:175], v[44:47]
	v_mfma_f32_16x16x32_bf16 v[32:35], v[68:71], v[180:183], v[32:35]
	v_mfma_f32_16x16x32_bf16 v[28:31], v[92:95], v[180:183], v[28:31]
	v_mfma_f32_16x16x32_bf16 v[16:19], v[68:71], v[188:191], v[16:19]
	v_mfma_f32_16x16x32_bf16 v[12:15], v[92:95], v[188:191], v[12:15]
	v_mfma_f32_16x16x32_bf16 v[64:67], v[80:83], v[168:171], v[64:67]
	v_mfma_f32_16x16x32_bf16 v[60:63], v[100:103], v[168:171], v[60:63]
	v_mfma_f32_16x16x32_bf16 v[48:51], v[80:83], v[176:179], v[48:51]
	v_mfma_f32_16x16x32_bf16 v[44:47], v[100:103], v[176:179], v[44:47]
	v_mfma_f32_16x16x32_bf16 v[32:35], v[80:83], v[184:187], v[32:35]
	v_mfma_f32_16x16x32_bf16 v[28:31], v[100:103], v[184:187], v[28:31]
	v_mfma_f32_16x16x32_bf16 v[16:19], v[80:83], v[208:211], v[16:19]
	v_mfma_f32_16x16x32_bf16 v[12:15], v[100:103], v[208:211], v[12:15]
	s_setprio 0
	s_setprio 1
	v_mfma_f32_16x16x32_bf16 v[56:59], v[112:115], v[156:159], v[56:59]
	v_mfma_f32_16x16x32_bf16 v[52:55], v[132:135], v[156:159], v[52:55]
	v_mfma_f32_16x16x32_bf16 v[40:43], v[112:115], v[172:175], v[40:43]
	v_mfma_f32_16x16x32_bf16 v[36:39], v[132:135], v[172:175], v[36:39]
	v_mfma_f32_16x16x32_bf16 v[24:27], v[112:115], v[180:183], v[24:27]
	v_mfma_f32_16x16x32_bf16 v[20:23], v[132:135], v[180:183], v[20:23]
	v_mfma_f32_16x16x32_bf16 v[8:11], v[112:115], v[188:191], v[8:11]
	v_mfma_f32_16x16x32_bf16 v[4:7], v[132:135], v[188:191], v[4:7]
	v_mfma_f32_16x16x32_bf16 v[56:59], v[120:123], v[168:171], v[56:59]
	v_mfma_f32_16x16x32_bf16 v[52:55], v[144:147], v[168:171], v[52:55]
	v_mfma_f32_16x16x32_bf16 v[40:43], v[120:123], v[176:179], v[40:43]
	v_mfma_f32_16x16x32_bf16 v[36:39], v[144:147], v[176:179], v[36:39]
	v_mfma_f32_16x16x32_bf16 v[24:27], v[120:123], v[184:187], v[24:27]
	v_mfma_f32_16x16x32_bf16 v[20:23], v[144:147], v[184:187], v[20:23]
	v_mfma_f32_16x16x32_bf16 v[8:11], v[120:123], v[208:211], v[8:11]
	v_mfma_f32_16x16x32_bf16 v[4:7], v[144:147], v[208:211], v[4:7]
	s_setprio 0
	s_barrier
	s_add_i32 s53, s53, 2
	s_cmp_gt_u32 s53, 41
	s_cbranch_scc0 .LBB0_480
	s_and_b64 vcc, exec, s[20:21]
	s_cbranch_vccz .LBB0_483
	s_barrier
